# GEMM tile loops: first K iteration peeled with C=0 MFMAs, accumulator zeroing v_movs removed (gate/up, QKV, S5-in, GLU)
# speedup vs baseline: 1.0073x; 1.0055x over previous
.LBB0_48:
	s_ashr_i32 s13, s12, 31
	v_cmp_lt_i64_e32 vcc, s[16:17], v[162:163]
	s_lshl_b64 s[16:17], s[12:13], 19
	s_add_u32 s16, s8, s16
	s_addc_u32 s17, s9, s17
	s_and_b64 s[18:19], vcc, exec
	s_cselect_b32 s13, s17, s23
	s_cselect_b32 s67, s16, s22
	s_ashr_i32 s11, s10, 31
	s_lshl_b64 s[18:19], s[10:11], 19
	s_add_u32 s18, s31, s18
	s_addc_u32 s19, s35, s19
	s_and_b64 s[62:63], vcc, exec
	s_cselect_b32 s11, s19, s59
	s_cselect_b32 s68, s18, s58
	s_add_u32 s22, s22, 0x40080
	s_addc_u32 s23, s23, 0
	s_add_u32 s69, s58, 0x100
	s_addc_u32 s72, s59, 0
	s_mov_b32 s73, -2
	s_waitcnt lgkmcnt(0)
	s_add_u32 s2, s22, 0xfffc0080
	s_addc_u32 s15, s23, -1
	s_add_i32 s74, 0, 0x10000
	v_add_u32_e32 v150, s74, v153
	ds_read_b128 v[128:131], v150
	ds_read_b128 v[132:135], v150 offset:1024
	ds_read_b128 v[136:139], v150 offset:2048
	ds_read_b128 v[166:169], v150 offset:3072
	s_cmp_eq_u32 s73, 12
	s_cselect_b32 s63, s13, s15
	s_cselect_b32 s62, s67, s2
	s_cselect_b32 s59, s11, s72
	s_cselect_b32 s58, s68, s69
	v_lshl_add_u64 v[150:151], s[22:23], 0, v[146:147]
	s_add_i32 m0, s21, 0xc000
	ds_read_b128 v[170:173], v155
	ds_read_b128 v[174:177], v155 offset:1024
	ds_read_b128 v[178:181], v155 offset:2048
	ds_read_b128 v[182:185], v155 offset:3072
	ds_read_b128 v[186:189], v155 offset:4096
	ds_read_b128 v[214:217], v155 offset:5120
	ds_read_b128 v[218:221], v155 offset:6144
	ds_read_b128 v[222:225], v155 offset:7168
	global_load_lds_dwordx4 v[150:151], off
	v_lshl_add_u64 v[150:151], s[22:23], 0, v[148:149]
	s_add_i32 m0, s21, 0xe000
	s_nop 0
	global_load_lds_dwordx4 v[150:151], off
	s_waitcnt lgkmcnt(8)
	s_barrier
	s_waitcnt lgkmcnt(0)
	s_setprio 1
	s_waitcnt lgkmcnt(0)
	v_mfma_f32_16x16x32_bf16 v[124:127], v[128:131], v[170:173], 0
	v_mfma_f32_16x16x32_bf16 v[120:123], v[136:139], v[170:173], 0
	v_mfma_f32_16x16x32_bf16 v[108:111], v[128:131], v[178:181], 0
	v_mfma_f32_16x16x32_bf16 v[104:107], v[136:139], v[178:181], 0
	v_mfma_f32_16x16x32_bf16 v[92:95], v[128:131], v[186:189], 0
	v_mfma_f32_16x16x32_bf16 v[88:91], v[136:139], v[186:189], 0
	v_mfma_f32_16x16x32_bf16 v[76:79], v[128:131], v[218:221], 0
	v_mfma_f32_16x16x32_bf16 v[72:75], v[136:139], v[218:221], 0
	v_mfma_f32_16x16x32_bf16 v[124:127], v[132:135], v[174:177], v[124:127]
	v_mfma_f32_16x16x32_bf16 v[120:123], v[166:169], v[174:177], v[120:123]
	v_mfma_f32_16x16x32_bf16 v[108:111], v[132:135], v[182:185], v[108:111]
	v_mfma_f32_16x16x32_bf16 v[104:107], v[166:169], v[182:185], v[104:107]
	v_mfma_f32_16x16x32_bf16 v[92:95], v[132:135], v[214:217], v[92:95]
	v_mfma_f32_16x16x32_bf16 v[88:91], v[166:169], v[214:217], v[88:91]
	v_mfma_f32_16x16x32_bf16 v[76:79], v[132:135], v[222:225], v[76:79]
	v_mfma_f32_16x16x32_bf16 v[72:75], v[166:169], v[222:225], v[72:75]
	s_setprio 0
	s_barrier
	s_add_i32 s2, 0, 0x14000
	v_add_u32_e32 v150, s2, v153
	s_add_i32 s15, s74, s39
	ds_read_b128 v[226:229], v150
	ds_read_b128 v[230:233], v150 offset:1024
	ds_read_b128 v[234:237], v150 offset:2048
	ds_read_b128 v[238:241], v150 offset:3072
	v_lshl_add_u64 v[150:151], s[58:59], 0, v[158:159]
	s_mov_b32 m0, s15
	v_lshl_add_u64 v[190:191], s[58:59], 0, v[144:145]
	global_load_lds_dwordx4 v[150:151], off
	s_add_i32 m0, s15, 0x2000
	s_nop 0
	global_load_lds_dwordx4 v[190:191], off
	s_barrier
	s_waitcnt lgkmcnt(0)
	s_setprio 1
	s_waitcnt lgkmcnt(0)
	v_mfma_f32_16x16x32_bf16 v[116:119], v[226:229], v[170:173], 0
	v_mfma_f32_16x16x32_bf16 v[112:115], v[234:237], v[170:173], 0
	v_mfma_f32_16x16x32_bf16 v[100:103], v[226:229], v[178:181], 0
	v_mfma_f32_16x16x32_bf16 v[96:99], v[234:237], v[178:181], 0
	v_mfma_f32_16x16x32_bf16 v[84:87], v[226:229], v[186:189], 0
	v_mfma_f32_16x16x32_bf16 v[80:83], v[234:237], v[186:189], 0
	v_mfma_f32_16x16x32_bf16 v[68:71], v[226:229], v[218:221], 0
	v_mfma_f32_16x16x32_bf16 v[64:67], v[234:237], v[218:221], 0
	v_mfma_f32_16x16x32_bf16 v[116:119], v[230:233], v[174:177], v[116:119]
	v_mfma_f32_16x16x32_bf16 v[112:115], v[238:241], v[174:177], v[112:115]
	v_mfma_f32_16x16x32_bf16 v[100:103], v[230:233], v[182:185], v[100:103]
	v_mfma_f32_16x16x32_bf16 v[96:99], v[238:241], v[182:185], v[96:99]
	v_mfma_f32_16x16x32_bf16 v[84:87], v[230:233], v[214:217], v[84:87]
	v_mfma_f32_16x16x32_bf16 v[80:83], v[238:241], v[214:217], v[80:83]
	v_mfma_f32_16x16x32_bf16 v[68:71], v[230:233], v[222:225], v[68:71]
	v_mfma_f32_16x16x32_bf16 v[64:67], v[238:241], v[222:225], v[64:67]
	s_setprio 0
	s_mov_b32 m0, s21
	v_lshl_add_u64 v[202:203], s[62:63], 0, v[140:141]
	s_barrier
	ds_read_b128 v[170:173], v155 offset:16384
	ds_read_b128 v[174:177], v155 offset:17408
	ds_read_b128 v[178:181], v155 offset:18432
	ds_read_b128 v[182:185], v155 offset:19456
	ds_read_b128 v[186:189], v155 offset:20480
	ds_read_b128 v[214:217], v155 offset:21504
	ds_read_b128 v[218:221], v155 offset:22528
	ds_read_b128 v[222:225], v155 offset:23552
	global_load_lds_dwordx4 v[202:203], off
	v_lshl_add_u64 v[204:205], s[62:63], 0, v[142:143]
	s_mov_b32 m0, s43
	s_nop 0
	global_load_lds_dwordx4 v[204:205], off
	s_barrier
	s_waitcnt lgkmcnt(0)
	s_setprio 1
	s_waitcnt lgkmcnt(0)
	v_mfma_f32_16x16x32_bf16 v[60:63], v[128:131], v[170:173], 0
	v_mfma_f32_16x16x32_bf16 v[56:59], v[136:139], v[170:173], 0
	v_mfma_f32_16x16x32_bf16 v[44:47], v[128:131], v[178:181], 0
	v_mfma_f32_16x16x32_bf16 v[40:43], v[136:139], v[178:181], 0
	v_mfma_f32_16x16x32_bf16 v[28:31], v[128:131], v[186:189], 0
	v_mfma_f32_16x16x32_bf16 v[24:27], v[136:139], v[186:189], 0
	v_mfma_f32_16x16x32_bf16 v[12:15], v[128:131], v[218:221], 0
	v_mfma_f32_16x16x32_bf16 v[8:11], v[136:139], v[218:221], 0
	v_mfma_f32_16x16x32_bf16 v[60:63], v[132:135], v[174:177], v[60:63]
	v_mfma_f32_16x16x32_bf16 v[56:59], v[166:169], v[174:177], v[56:59]
	v_mfma_f32_16x16x32_bf16 v[44:47], v[132:135], v[182:185], v[44:47]
	v_mfma_f32_16x16x32_bf16 v[40:43], v[166:169], v[182:185], v[40:43]
	v_mfma_f32_16x16x32_bf16 v[28:31], v[132:135], v[214:217], v[28:31]
	v_mfma_f32_16x16x32_bf16 v[24:27], v[166:169], v[214:217], v[24:27]
	v_mfma_f32_16x16x32_bf16 v[12:15], v[132:135], v[222:225], v[12:15]
	v_mfma_f32_16x16x32_bf16 v[8:11], v[166:169], v[222:225], v[8:11]
	s_setprio 0
	s_barrier
	s_add_u32 s74, s58, 0x40000
	s_addc_u32 s75, s59, 0
	s_add_i32 s2, s2, s39
	v_lshl_add_u64 v[128:129], s[74:75], 0, v[158:159]
	s_mov_b32 m0, s2
	s_nop 0
	global_load_lds_dwordx4 v[128:129], off
	v_lshl_add_u64 v[128:129], s[74:75], 0, v[144:145]
	s_add_i32 m0, s2, 0x2000
	s_nop 0
	global_load_lds_dwordx4 v[128:129], off
	s_waitcnt vmcnt(6)
	s_barrier
	s_setprio 1
	v_mfma_f32_16x16x32_bf16 v[52:55], v[226:229], v[170:173], 0
	v_mfma_f32_16x16x32_bf16 v[48:51], v[234:237], v[170:173], 0
	v_mfma_f32_16x16x32_bf16 v[36:39], v[226:229], v[178:181], 0
	v_mfma_f32_16x16x32_bf16 v[32:35], v[234:237], v[178:181], 0
	v_mfma_f32_16x16x32_bf16 v[20:23], v[226:229], v[186:189], 0
	v_mfma_f32_16x16x32_bf16 v[16:19], v[234:237], v[186:189], 0
	v_mfma_f32_16x16x32_bf16 v[4:7], v[226:229], v[218:221], 0
	v_mfma_f32_16x16x32_bf16 v[0:3], v[234:237], v[218:221], 0
	v_mfma_f32_16x16x32_bf16 v[52:55], v[230:233], v[174:177], v[52:55]
	v_mfma_f32_16x16x32_bf16 v[48:51], v[238:241], v[174:177], v[48:51]
	v_mfma_f32_16x16x32_bf16 v[36:39], v[230:233], v[182:185], v[36:39]
	v_mfma_f32_16x16x32_bf16 v[32:35], v[238:241], v[182:185], v[32:35]
	v_mfma_f32_16x16x32_bf16 v[20:23], v[230:233], v[214:217], v[20:23]
	v_mfma_f32_16x16x32_bf16 v[16:19], v[238:241], v[214:217], v[16:19]
	v_mfma_f32_16x16x32_bf16 v[4:7], v[230:233], v[222:225], v[4:7]
	v_mfma_f32_16x16x32_bf16 v[0:3], v[238:241], v[222:225], v[0:3]
	s_setprio 0
	s_add_i32 s2, 0, 0x18000
	v_add_u32_e32 v165, s2, v153
	s_barrier
	ds_read_b128 v[128:131], v165
	ds_read_b128 v[132:135], v165 offset:1024
	ds_read_b128 v[136:139], v165 offset:2048
	ds_read_b128 v[166:169], v165 offset:3072
	s_add_u32 s62, s62, 0x40000
	s_addc_u32 s63, s63, 0
	s_mov_b32 m0, s47
	v_lshl_add_u64 v[226:227], s[62:63], 0, v[140:141]
	ds_read_b128 v[170:173], v155 offset:32768
	ds_read_b128 v[174:177], v155 offset:33792
	ds_read_b128 v[178:181], v155 offset:34816
	ds_read_b128 v[182:185], v155 offset:35840
	ds_read_b128 v[186:189], v155 offset:36864
	ds_read_b128 v[214:217], v155 offset:37888
	ds_read_b128 v[218:221], v155 offset:38912
	ds_read_b128 v[222:225], v155 offset:39936
	global_load_lds_dwordx4 v[226:227], off
	v_lshl_add_u64 v[226:227], s[62:63], 0, v[142:143]
	s_mov_b32 m0, s48
	s_nop 0
	global_load_lds_dwordx4 v[226:227], off
	s_waitcnt lgkmcnt(8)
	s_barrier
	s_waitcnt lgkmcnt(0)
	s_setprio 1
	s_waitcnt lgkmcnt(0)
	v_mfma_f32_16x16x32_bf16 v[124:127], v[128:131], v[170:173], v[124:127]
	v_mfma_f32_16x16x32_bf16 v[120:123], v[136:139], v[170:173], v[120:123]
	v_mfma_f32_16x16x32_bf16 v[108:111], v[128:131], v[178:181], v[108:111]
	v_mfma_f32_16x16x32_bf16 v[104:107], v[136:139], v[178:181], v[104:107]
	v_mfma_f32_16x16x32_bf16 v[92:95], v[128:131], v[186:189], v[92:95]
	v_mfma_f32_16x16x32_bf16 v[88:91], v[136:139], v[186:189], v[88:91]
	v_mfma_f32_16x16x32_bf16 v[76:79], v[128:131], v[218:221], v[76:79]
	v_mfma_f32_16x16x32_bf16 v[72:75], v[136:139], v[218:221], v[72:75]
	v_mfma_f32_16x16x32_bf16 v[124:127], v[132:135], v[174:177], v[124:127]
	v_mfma_f32_16x16x32_bf16 v[120:123], v[166:169], v[174:177], v[120:123]
	v_mfma_f32_16x16x32_bf16 v[108:111], v[132:135], v[182:185], v[108:111]
	v_mfma_f32_16x16x32_bf16 v[104:107], v[166:169], v[182:185], v[104:107]
	v_mfma_f32_16x16x32_bf16 v[92:95], v[132:135], v[214:217], v[92:95]
	v_mfma_f32_16x16x32_bf16 v[88:91], v[166:169], v[214:217], v[88:91]
	v_mfma_f32_16x16x32_bf16 v[76:79], v[132:135], v[222:225], v[76:79]
	v_mfma_f32_16x16x32_bf16 v[72:75], v[166:169], v[222:225], v[72:75]
	s_setprio 0
	s_barrier
	s_add_i32 s15, 0, 0x1c000
	s_add_i32 s2, s2, s39
	v_add_u32_e32 v165, s15, v153
	v_lshl_add_u64 v[150:151], v[150:151], 0, s[70:71]
	s_mov_b32 m0, s2
	ds_read_b128 v[226:229], v165
	ds_read_b128 v[230:233], v165 offset:1024
	ds_read_b128 v[234:237], v165 offset:2048
	ds_read_b128 v[238:241], v165 offset:3072
	global_load_lds_dwordx4 v[150:151], off
	v_lshl_add_u64 v[150:151], v[190:191], 0, s[70:71]
	s_add_i32 m0, s2, 0x2000
	s_nop 0
	global_load_lds_dwordx4 v[150:151], off
	s_barrier
	s_waitcnt lgkmcnt(0)
	s_setprio 1
	s_waitcnt lgkmcnt(0)
	v_mfma_f32_16x16x32_bf16 v[116:119], v[226:229], v[170:173], v[116:119]
	v_mfma_f32_16x16x32_bf16 v[112:115], v[234:237], v[170:173], v[112:115]
	v_mfma_f32_16x16x32_bf16 v[100:103], v[226:229], v[178:181], v[100:103]
	v_mfma_f32_16x16x32_bf16 v[96:99], v[234:237], v[178:181], v[96:99]
	v_mfma_f32_16x16x32_bf16 v[84:87], v[226:229], v[186:189], v[84:87]
	v_mfma_f32_16x16x32_bf16 v[80:83], v[234:237], v[186:189], v[80:83]
	v_mfma_f32_16x16x32_bf16 v[68:71], v[226:229], v[218:221], v[68:71]
	v_mfma_f32_16x16x32_bf16 v[64:67], v[234:237], v[218:221], v[64:67]
	v_mfma_f32_16x16x32_bf16 v[116:119], v[230:233], v[174:177], v[116:119]
	v_mfma_f32_16x16x32_bf16 v[112:115], v[238:241], v[174:177], v[112:115]
	v_mfma_f32_16x16x32_bf16 v[100:103], v[230:233], v[182:185], v[100:103]
	v_mfma_f32_16x16x32_bf16 v[96:99], v[238:241], v[182:185], v[96:99]
	v_mfma_f32_16x16x32_bf16 v[84:87], v[230:233], v[214:217], v[84:87]
	v_mfma_f32_16x16x32_bf16 v[80:83], v[238:241], v[214:217], v[80:83]
	v_mfma_f32_16x16x32_bf16 v[68:71], v[230:233], v[222:225], v[68:71]
	v_mfma_f32_16x16x32_bf16 v[64:67], v[238:241], v[222:225], v[64:67]
	s_setprio 0
	s_mov_b32 m0, s50
	v_lshl_add_u64 v[150:151], v[202:203], 0, s[70:71]
	s_barrier
	ds_read_b128 v[170:173], v155 offset:49152
	ds_read_b128 v[174:177], v155 offset:50176
	ds_read_b128 v[178:181], v155 offset:51200
	ds_read_b128 v[182:185], v155 offset:52224
	ds_read_b128 v[186:189], v155 offset:53248
	ds_read_b128 v[214:217], v155 offset:54272
	ds_read_b128 v[218:221], v155 offset:55296
	ds_read_b128 v[222:225], v155 offset:56320
	global_load_lds_dwordx4 v[150:151], off
	v_lshl_add_u64 v[150:151], v[204:205], 0, s[70:71]
	s_mov_b32 m0, s51
	s_nop 0
	global_load_lds_dwordx4 v[150:151], off
	s_barrier
	s_waitcnt lgkmcnt(0)
	s_setprio 1
	s_waitcnt lgkmcnt(0)
	v_mfma_f32_16x16x32_bf16 v[60:63], v[128:131], v[170:173], v[60:63]
	v_mfma_f32_16x16x32_bf16 v[56:59], v[136:139], v[170:173], v[56:59]
	v_mfma_f32_16x16x32_bf16 v[44:47], v[128:131], v[178:181], v[44:47]
	v_mfma_f32_16x16x32_bf16 v[40:43], v[136:139], v[178:181], v[40:43]
	v_mfma_f32_16x16x32_bf16 v[28:31], v[128:131], v[186:189], v[28:31]
	v_mfma_f32_16x16x32_bf16 v[24:27], v[136:139], v[186:189], v[24:27]
	v_mfma_f32_16x16x32_bf16 v[12:15], v[128:131], v[218:221], v[12:15]
	v_mfma_f32_16x16x32_bf16 v[8:11], v[136:139], v[218:221], v[8:11]
	v_mfma_f32_16x16x32_bf16 v[60:63], v[132:135], v[174:177], v[60:63]
	v_mfma_f32_16x16x32_bf16 v[56:59], v[166:169], v[174:177], v[56:59]
	v_mfma_f32_16x16x32_bf16 v[44:47], v[132:135], v[182:185], v[44:47]
	v_mfma_f32_16x16x32_bf16 v[40:43], v[166:169], v[182:185], v[40:43]
	v_mfma_f32_16x16x32_bf16 v[28:31], v[132:135], v[214:217], v[28:31]
	v_mfma_f32_16x16x32_bf16 v[24:27], v[166:169], v[214:217], v[24:27]
	v_mfma_f32_16x16x32_bf16 v[12:15], v[132:135], v[222:225], v[12:15]
	v_mfma_f32_16x16x32_bf16 v[8:11], v[166:169], v[222:225], v[8:11]
	s_setprio 0
	s_barrier
	s_add_u32 s58, s58, 0x40080
	s_addc_u32 s59, s59, 0
	s_add_i32 s2, s15, s39
	v_lshl_add_u64 v[128:129], s[58:59], 0, v[158:159]
	s_mov_b32 m0, s2
	s_nop 0
	global_load_lds_dwordx4 v[128:129], off
	v_lshl_add_u64 v[128:129], s[58:59], 0, v[144:145]
	s_add_i32 m0, s2, 0x2000
	s_nop 0
	global_load_lds_dwordx4 v[128:129], off
	s_waitcnt vmcnt(6)
	s_barrier
	s_setprio 1
	v_mfma_f32_16x16x32_bf16 v[52:55], v[226:229], v[170:173], v[52:55]
	v_mfma_f32_16x16x32_bf16 v[48:51], v[234:237], v[170:173], v[48:51]
	v_mfma_f32_16x16x32_bf16 v[36:39], v[226:229], v[178:181], v[36:39]
	v_mfma_f32_16x16x32_bf16 v[32:35], v[234:237], v[178:181], v[32:35]
	v_mfma_f32_16x16x32_bf16 v[20:23], v[226:229], v[186:189], v[20:23]
	v_mfma_f32_16x16x32_bf16 v[16:19], v[234:237], v[186:189], v[16:19]
	v_mfma_f32_16x16x32_bf16 v[4:7], v[226:229], v[218:221], v[4:7]
	v_mfma_f32_16x16x32_bf16 v[0:3], v[234:237], v[218:221], v[0:3]
	v_mfma_f32_16x16x32_bf16 v[52:55], v[230:233], v[174:177], v[52:55]
	v_mfma_f32_16x16x32_bf16 v[48:51], v[238:241], v[174:177], v[48:51]
	v_mfma_f32_16x16x32_bf16 v[36:39], v[230:233], v[182:185], v[36:39]
	v_mfma_f32_16x16x32_bf16 v[32:35], v[238:241], v[182:185], v[32:35]
	v_mfma_f32_16x16x32_bf16 v[20:23], v[230:233], v[214:217], v[20:23]
	v_mfma_f32_16x16x32_bf16 v[16:19], v[238:241], v[214:217], v[16:19]
	v_mfma_f32_16x16x32_bf16 v[4:7], v[230:233], v[222:225], v[4:7]
	v_mfma_f32_16x16x32_bf16 v[0:3], v[238:241], v[222:225], v[0:3]
	s_setprio 0
	s_add_i32 s73, s73, 2
	s_add_u32 s22, s22, 0x100
	s_addc_u32 s23, s23, 0
	s_add_u32 s69, s69, 0x100
	s_addc_u32 s72, s72, 0
	s_cmp_gt_u32 s73, 13
	s_barrier
	s_cbranch_scc1 .Lzp_exit0

.Lzp_exit0:
	v_lshl_add_u32 v128, s20, 8, v152
	v_lshl_or_b32 v130, s66, 8, v154
	v_ashrrev_i32_e32 v131, 31, v130
	v_ashrrev_i32_e32 v129, 31, v128
	v_lshl_add_u64 v[132:133], v[130:131], 1, s[8:9]
	v_lshlrev_b64 v[134:135], 11, v[128:129]
	v_lshl_add_u64 v[150:151], v[132:133], 0, v[134:135]
	global_load_dwordx4 v[166:169], v[150:151], off
	global_load_dwordx4 v[170:173], v[150:151], off offset:256
	v_mul_f32_e32 v131, 0xbfb8aa3b, v120
	v_mul_f32_e32 v121, 0xbfb8aa3b, v121
	v_mul_f32_e32 v134, 0xbfb8aa3b, v122
	v_mul_f32_e32 v123, 0xbfb8aa3b, v123
	v_or_b32_e32 v120, 16, v128
	v_or_b32_e32 v122, 32, v128
	v_mul_f32_e32 v129, 0xbfb8aa3b, v124
	v_mul_f32_e32 v125, 0xbfb8aa3b, v125
	v_or_b32_e32 v124, 48, v128
	v_exp_f32_e32 v184, v121
	v_exp_f32_e32 v186, v123
	v_ashrrev_i32_e32 v121, 31, v120
	v_ashrrev_i32_e32 v123, 31, v122
	v_exp_f32_e32 v180, v125
	v_ashrrev_i32_e32 v125, 31, v124
	v_lshlrev_b64 v[120:121], 11, v[120:121]
	v_lshlrev_b64 v[122:123], 11, v[122:123]
	v_mul_f32_e32 v126, 0xbfb8aa3b, v126
	v_mul_f32_e32 v127, 0xbfb8aa3b, v127
	v_mul_f32_e32 v116, 0xbfb8aa3b, v116
	v_lshlrev_b32_e32 v130, 1, v130
	v_lshlrev_b64 v[124:125], 11, v[124:125]
	v_lshl_add_u64 v[120:121], v[132:133], 0, v[120:121]
	v_lshl_add_u64 v[122:123], v[132:133], 0, v[122:123]
	v_exp_f32_e32 v165, v129
	v_exp_f32_e32 v181, v126
	v_exp_f32_e32 v182, v127
	v_exp_f32_e32 v183, v131
	v_exp_f32_e32 v185, v134
	v_exp_f32_e32 v187, v116
	v_lshl_add_u32 v116, v128, 11, v130
	v_lshl_add_u64 v[178:179], v[132:133], 0, v[124:125]
	global_load_dwordx4 v[174:177], v[120:121], off
	global_load_dwordx4 v[136:139], v[120:121], off offset:256
	global_load_dwordx4 v[132:135], v[122:123], off
	global_load_dwordx4 v[128:131], v[122:123], off offset:256
	global_load_dwordx4 v[124:127], v[178:179], off
	s_nop 0
	global_load_dwordx4 v[120:123], v[178:179], off offset:256
	v_mul_f32_e32 v117, 0xbfb8aa3b, v117
	v_exp_f32_e32 v117, v117
	v_add_f32_e32 v178, 1.0, v180
	v_add_f32_e32 v165, 1.0, v165
	v_add_f32_e32 v180, 1.0, v182
	v_add_f32_e32 v182, 1.0, v184
	v_add_f32_e32 v184, 1.0, v186
	v_rcp_f32_e32 v178, v178
	v_add_f32_e32 v179, 1.0, v181
	v_add_f32_e32 v181, 1.0, v183
	v_add_f32_e32 v183, 1.0, v185
	v_rcp_f32_e32 v165, v165
	v_rcp_f32_e32 v180, v180
	v_rcp_f32_e32 v182, v182
	v_rcp_f32_e32 v184, v184
	v_rcp_f32_e32 v179, v179
	v_rcp_f32_e32 v181, v181
	v_rcp_f32_e32 v183, v183
	v_add_f32_e32 v117, 1.0, v117
	v_add_f32_e32 v185, 1.0, v187
	v_rcp_f32_e32 v117, v117
	v_mul_f32_e32 v118, 0xbfb8aa3b, v118
	v_rcp_f32_e32 v185, v185
	v_exp_f32_e32 v118, v118
	v_mul_f32_e32 v119, 0xbfb8aa3b, v119
	v_exp_f32_e32 v119, v119
	v_mul_f32_e32 v112, 0xbfb8aa3b, v112
	v_exp_f32_e32 v112, v112
	v_mul_f32_e32 v113, 0xbfb8aa3b, v113
	v_exp_f32_e32 v113, v113
	v_mul_f32_e32 v114, 0xbfb8aa3b, v114
	v_add_f32_e32 v112, 1.0, v112
	v_rcp_f32_e32 v112, v112
	v_add_f32_e32 v113, 1.0, v113
	v_rcp_f32_e32 v113, v113
	v_exp_f32_e32 v114, v114
	v_mul_f32_e32 v115, 0xbfb8aa3b, v115
	v_exp_f32_e32 v115, v115
	v_mul_f32_e32 v108, 0xbfb8aa3b, v108
	v_exp_f32_e32 v108, v108
	v_mul_f32_e32 v109, 0xbfb8aa3b, v109
	v_exp_f32_e32 v109, v109
	v_mul_f32_e32 v110, 0xbfb8aa3b, v110
	v_add_f32_e32 v108, 1.0, v108
	v_rcp_f32_e32 v108, v108
	s_waitcnt vmcnt(0)
	v_lshlrev_b32_e32 v186, 16, v166
	v_and_b32_e32 v166, 0xffff0000, v166
	v_lshlrev_b32_e32 v187, 16, v167
	v_and_b32_e32 v167, 0xffff0000, v167
	v_lshlrev_b32_e32 v188, 16, v168
	v_and_b32_e32 v168, 0xffff0000, v168
	v_lshlrev_b32_e32 v189, 16, v169
	v_and_b32_e32 v169, 0xffff0000, v169
	v_mul_f32_e32 v166, v178, v166
	v_mul_f32_e32 v165, v165, v186
	v_mul_f32_e32 v167, v180, v167
	v_mul_f32_e32 v168, v182, v168
	v_mul_f32_e32 v169, v184, v169
	v_cvt_pk_bf16_f32 v166, v165, v166
	v_mul_f32_e32 v178, v179, v187
	v_mul_f32_e32 v179, v181, v188
	v_mul_f32_e32 v180, v183, v189
	v_cvt_pk_bf16_f32 v167, v178, v167
	v_cvt_pk_bf16_f32 v168, v179, v168
	v_cvt_pk_bf16_f32 v169, v180, v169
	buffer_store_dwordx4 v[166:169], v116, s[24:27], 0 offen sc1
	v_lshlrev_b32_e32 v165, 16, v170
	v_mul_f32_e32 v165, v185, v165
	v_and_b32_e32 v166, 0xffff0000, v170
	v_mul_f32_e32 v117, v117, v166
	v_cvt_pk_bf16_f32 v166, v165, v117
	v_add_f32_e32 v117, 1.0, v118
	v_rcp_f32_e32 v117, v117
	v_add_f32_e32 v118, 1.0, v119
	v_rcp_f32_e32 v118, v118
	v_lshlrev_b32_e32 v119, 16, v171
	v_mul_f32_e32 v117, v117, v119
	v_and_b32_e32 v119, 0xffff0000, v171
	v_mul_f32_e32 v118, v118, v119
	v_cvt_pk_bf16_f32 v167, v117, v118
	v_lshlrev_b32_e32 v117, 16, v172
	v_mul_f32_e32 v112, v112, v117
	v_and_b32_e32 v117, 0xffff0000, v172
	v_mul_f32_e32 v113, v113, v117
	v_cvt_pk_bf16_f32 v168, v112, v113
	v_add_f32_e32 v112, 1.0, v114
	v_rcp_f32_e32 v112, v112
	v_add_f32_e32 v113, 1.0, v115
	v_rcp_f32_e32 v113, v113
	v_lshlrev_b32_e32 v114, 16, v173
	v_add_f32_e32 v109, 1.0, v109
	v_mul_f32_e32 v112, v112, v114
	v_and_b32_e32 v114, 0xffff0000, v173
	v_rcp_f32_e32 v109, v109
	v_mul_f32_e32 v113, v113, v114
	v_exp_f32_e32 v110, v110
	v_mul_f32_e32 v111, 0xbfb8aa3b, v111
	v_cvt_pk_bf16_f32 v169, v112, v113
	v_lshlrev_b32_e32 v113, 16, v174
	v_exp_f32_e32 v111, v111
	v_mul_f32_e32 v108, v108, v113
	v_and_b32_e32 v113, 0xffff0000, v174
	v_mul_f32_e32 v104, 0xbfb8aa3b, v104
	v_mul_f32_e32 v109, v109, v113
	v_exp_f32_e32 v104, v104
	v_mul_f32_e32 v105, 0xbfb8aa3b, v105
	buffer_store_dwordx4 v[166:169], v116, s[24:27], 0 offen offset:256 sc1
	v_cvt_pk_bf16_f32 v108, v108, v109
	v_add_f32_e32 v109, 1.0, v110
	v_exp_f32_e32 v105, v105
	v_rcp_f32_e32 v109, v109
	v_add_f32_e32 v110, 1.0, v111
	v_rcp_f32_e32 v110, v110
	v_add_f32_e32 v104, 1.0, v104
	v_lshlrev_b32_e32 v111, 16, v175
	v_rcp_f32_e32 v104, v104
	v_add_f32_e32 v105, 1.0, v105
	v_mul_f32_e32 v106, 0xbfb8aa3b, v106
	v_mul_f32_e32 v109, v109, v111
	v_and_b32_e32 v111, 0xffff0000, v175
	v_rcp_f32_e32 v105, v105
	v_exp_f32_e32 v106, v106
	v_mul_f32_e32 v107, 0xbfb8aa3b, v107
	v_mul_f32_e32 v110, v110, v111
	v_exp_f32_e32 v107, v107
	v_mul_f32_e32 v100, 0xbfb8aa3b, v100
	v_cvt_pk_bf16_f32 v109, v109, v110
	v_lshlrev_b32_e32 v110, 16, v176
	v_exp_f32_e32 v100, v100
	v_mul_f32_e32 v101, 0xbfb8aa3b, v101
	v_mul_f32_e32 v104, v104, v110
	v_and_b32_e32 v110, 0xffff0000, v176
	v_exp_f32_e32 v101, v101
	v_mul_f32_e32 v105, v105, v110
	v_cvt_pk_bf16_f32 v110, v104, v105
	v_add_f32_e32 v104, 1.0, v106
	v_rcp_f32_e32 v104, v104
	v_add_f32_e32 v105, 1.0, v107
	v_rcp_f32_e32 v105, v105
	v_add_f32_e32 v100, 1.0, v100
	v_rcp_f32_e32 v100, v100
	v_add_f32_e32 v101, 1.0, v101
	v_lshlrev_b32_e32 v106, 16, v177
	v_rcp_f32_e32 v101, v101
	v_mul_f32_e32 v102, 0xbfb8aa3b, v102
	v_mul_f32_e32 v104, v104, v106
	v_and_b32_e32 v106, 0xffff0000, v177
	v_exp_f32_e32 v102, v102
	v_mul_f32_e32 v103, 0xbfb8aa3b, v103
	v_mul_f32_e32 v105, v105, v106
	v_cvt_pk_bf16_f32 v111, v104, v105
	v_lshlrev_b32_e32 v104, 16, v136
	v_exp_f32_e32 v103, v103
	v_mul_f32_e32 v100, v100, v104
	v_and_b32_e32 v104, 0xffff0000, v136
	v_mul_f32_e32 v96, 0xbfb8aa3b, v96
	v_add_u32_e32 v112, 0x8000, v116
	v_mul_f32_e32 v101, v101, v104
	v_exp_f32_e32 v96, v96
	v_mul_f32_e32 v97, 0xbfb8aa3b, v97
	buffer_store_dwordx4 v[108:111], v112, s[24:27], 0 offen sc1
	v_cvt_pk_bf16_f32 v100, v100, v101
	v_add_f32_e32 v101, 1.0, v102
	v_exp_f32_e32 v97, v97
	v_rcp_f32_e32 v101, v101
	v_add_f32_e32 v102, 1.0, v103
	v_rcp_f32_e32 v102, v102
	v_add_f32_e32 v96, 1.0, v96
	v_lshlrev_b32_e32 v103, 16, v137
	v_rcp_f32_e32 v96, v96
	v_add_f32_e32 v97, 1.0, v97
	v_mul_f32_e32 v98, 0xbfb8aa3b, v98
	v_mul_f32_e32 v101, v101, v103
	v_and_b32_e32 v103, 0xffff0000, v137
	v_rcp_f32_e32 v97, v97
	v_exp_f32_e32 v98, v98
	v_mul_f32_e32 v99, 0xbfb8aa3b, v99
	v_mul_f32_e32 v102, v102, v103
	v_exp_f32_e32 v99, v99
	v_cvt_pk_bf16_f32 v101, v101, v102
	v_lshlrev_b32_e32 v102, 16, v138
	v_mul_f32_e32 v92, 0xbfb8aa3b, v92
	v_mul_f32_e32 v96, v96, v102
	v_and_b32_e32 v102, 0xffff0000, v138
	v_exp_f32_e32 v92, v92
	v_mul_f32_e32 v93, 0xbfb8aa3b, v93
	v_mul_f32_e32 v97, v97, v102
	v_cvt_pk_bf16_f32 v102, v96, v97
	v_add_f32_e32 v96, 1.0, v98
	v_exp_f32_e32 v93, v93
	v_rcp_f32_e32 v96, v96
	v_add_f32_e32 v97, 1.0, v99
	v_rcp_f32_e32 v97, v97
	v_add_f32_e32 v92, 1.0, v92
	v_lshlrev_b32_e32 v98, 16, v139
	v_rcp_f32_e32 v92, v92
	v_add_f32_e32 v93, 1.0, v93
	v_mul_f32_e32 v96, v96, v98
	v_and_b32_e32 v98, 0xffff0000, v139
	v_rcp_f32_e32 v93, v93
	v_mul_f32_e32 v94, 0xbfb8aa3b, v94
	v_mul_f32_e32 v97, v97, v98
	v_exp_f32_e32 v94, v94
	v_mul_f32_e32 v95, 0xbfb8aa3b, v95
	v_cvt_pk_bf16_f32 v103, v96, v97
	v_lshlrev_b32_e32 v97, 16, v132
	v_exp_f32_e32 v95, v95
	v_mul_f32_e32 v92, v92, v97
	v_and_b32_e32 v97, 0xffff0000, v132
	v_mul_f32_e32 v88, 0xbfb8aa3b, v88
	v_mul_f32_e32 v93, v93, v97
	v_exp_f32_e32 v88, v88
	v_mul_f32_e32 v89, 0xbfb8aa3b, v89
	buffer_store_dwordx4 v[100:103], v112, s[24:27], 0 offen offset:256 sc1
	v_cvt_pk_bf16_f32 v92, v92, v93
	v_add_f32_e32 v93, 1.0, v94
	v_exp_f32_e32 v89, v89
	v_rcp_f32_e32 v93, v93
	v_add_f32_e32 v94, 1.0, v95
	v_rcp_f32_e32 v94, v94
	v_add_f32_e32 v88, 1.0, v88
	v_lshlrev_b32_e32 v95, 16, v133
	v_rcp_f32_e32 v88, v88
	v_add_f32_e32 v89, 1.0, v89
	v_mul_f32_e32 v90, 0xbfb8aa3b, v90
	v_mul_f32_e32 v93, v93, v95
	v_and_b32_e32 v95, 0xffff0000, v133
	v_rcp_f32_e32 v89, v89
	v_exp_f32_e32 v90, v90
	v_mul_f32_e32 v91, 0xbfb8aa3b, v91
	v_mul_f32_e32 v94, v94, v95
	v_exp_f32_e32 v91, v91
	v_mul_f32_e32 v84, 0xbfb8aa3b, v84
	v_cvt_pk_bf16_f32 v93, v93, v94
	v_lshlrev_b32_e32 v94, 16, v134
	v_exp_f32_e32 v84, v84
	v_mul_f32_e32 v85, 0xbfb8aa3b, v85
	v_mul_f32_e32 v88, v88, v94
	v_and_b32_e32 v94, 0xffff0000, v134
	v_exp_f32_e32 v85, v85
	v_mul_f32_e32 v89, v89, v94
	v_cvt_pk_bf16_f32 v94, v88, v89
	v_add_f32_e32 v88, 1.0, v90
	v_rcp_f32_e32 v88, v88
	v_add_f32_e32 v89, 1.0, v91
	v_rcp_f32_e32 v89, v89
	v_add_f32_e32 v84, 1.0, v84
	v_rcp_f32_e32 v84, v84
	v_add_f32_e32 v85, 1.0, v85
	v_lshlrev_b32_e32 v90, 16, v135
	v_rcp_f32_e32 v85, v85
	v_mul_f32_e32 v86, 0xbfb8aa3b, v86
	v_mul_f32_e32 v88, v88, v90
	v_and_b32_e32 v90, 0xffff0000, v135
	v_exp_f32_e32 v86, v86
	v_mul_f32_e32 v87, 0xbfb8aa3b, v87
	v_mul_f32_e32 v89, v89, v90
	v_cvt_pk_bf16_f32 v95, v88, v89
	v_lshlrev_b32_e32 v88, 16, v128
	v_exp_f32_e32 v87, v87
	v_mul_f32_e32 v84, v84, v88
	v_and_b32_e32 v88, 0xffff0000, v128
	v_mul_f32_e32 v80, 0xbfb8aa3b, v80
	v_add_u32_e32 v96, 0x10000, v116
	v_mul_f32_e32 v85, v85, v88
	v_exp_f32_e32 v80, v80
	v_mul_f32_e32 v81, 0xbfb8aa3b, v81
	buffer_store_dwordx4 v[92:95], v96, s[24:27], 0 offen sc1
	v_cvt_pk_bf16_f32 v84, v84, v85
	v_add_f32_e32 v85, 1.0, v86
	v_exp_f32_e32 v81, v81
	v_rcp_f32_e32 v85, v85
	v_add_f32_e32 v86, 1.0, v87
	v_rcp_f32_e32 v86, v86
	v_add_f32_e32 v80, 1.0, v80
	v_lshlrev_b32_e32 v87, 16, v129
	v_rcp_f32_e32 v80, v80
	v_add_f32_e32 v81, 1.0, v81
	v_mul_f32_e32 v82, 0xbfb8aa3b, v82
	v_mul_f32_e32 v85, v85, v87
	v_and_b32_e32 v87, 0xffff0000, v129
	v_rcp_f32_e32 v81, v81
	v_exp_f32_e32 v82, v82
	v_mul_f32_e32 v83, 0xbfb8aa3b, v83
	v_mul_f32_e32 v86, v86, v87
	v_exp_f32_e32 v83, v83
	v_cvt_pk_bf16_f32 v85, v85, v86
	v_lshlrev_b32_e32 v86, 16, v130
	v_mul_f32_e32 v76, 0xbfb8aa3b, v76
	v_mul_f32_e32 v80, v80, v86
	v_and_b32_e32 v86, 0xffff0000, v130
	v_exp_f32_e32 v76, v76
	v_mul_f32_e32 v77, 0xbfb8aa3b, v77
	v_mul_f32_e32 v81, v81, v86
	v_cvt_pk_bf16_f32 v86, v80, v81
	v_add_f32_e32 v80, 1.0, v82
	v_exp_f32_e32 v77, v77
	v_rcp_f32_e32 v80, v80
	v_add_f32_e32 v81, 1.0, v83
	v_rcp_f32_e32 v81, v81
	v_add_f32_e32 v76, 1.0, v76
	v_lshlrev_b32_e32 v82, 16, v131
	v_rcp_f32_e32 v76, v76
	v_add_f32_e32 v77, 1.0, v77
	v_mul_f32_e32 v80, v80, v82
	v_and_b32_e32 v82, 0xffff0000, v131
	v_rcp_f32_e32 v77, v77
	v_mul_f32_e32 v78, 0xbfb8aa3b, v78
	v_mul_f32_e32 v81, v81, v82
	v_exp_f32_e32 v78, v78
	v_mul_f32_e32 v79, 0xbfb8aa3b, v79
	v_cvt_pk_bf16_f32 v87, v80, v81
	v_lshlrev_b32_e32 v81, 16, v124
	v_exp_f32_e32 v79, v79
	v_mul_f32_e32 v76, v76, v81
	v_and_b32_e32 v81, 0xffff0000, v124
	v_mul_f32_e32 v72, 0xbfb8aa3b, v72
	v_mul_f32_e32 v77, v77, v81
	v_exp_f32_e32 v72, v72
	v_mul_f32_e32 v73, 0xbfb8aa3b, v73
	buffer_store_dwordx4 v[84:87], v96, s[24:27], 0 offen offset:256 sc1
	v_cvt_pk_bf16_f32 v76, v76, v77
	v_add_f32_e32 v77, 1.0, v78
	v_exp_f32_e32 v73, v73
	v_rcp_f32_e32 v77, v77
	v_add_f32_e32 v78, 1.0, v79
	v_rcp_f32_e32 v78, v78
	v_add_f32_e32 v72, 1.0, v72
	v_lshlrev_b32_e32 v79, 16, v125
	v_rcp_f32_e32 v72, v72
	v_add_f32_e32 v73, 1.0, v73
	v_mul_f32_e32 v74, 0xbfb8aa3b, v74
	v_mul_f32_e32 v77, v77, v79
	v_and_b32_e32 v79, 0xffff0000, v125
	v_rcp_f32_e32 v73, v73
	v_exp_f32_e32 v74, v74
	v_mul_f32_e32 v75, 0xbfb8aa3b, v75
	v_mul_f32_e32 v78, v78, v79
	v_exp_f32_e32 v75, v75
	v_mul_f32_e32 v68, 0xbfb8aa3b, v68
	v_cvt_pk_bf16_f32 v77, v77, v78
	v_lshlrev_b32_e32 v78, 16, v126
	v_exp_f32_e32 v68, v68
	v_mul_f32_e32 v69, 0xbfb8aa3b, v69
	v_mul_f32_e32 v72, v72, v78
	v_and_b32_e32 v78, 0xffff0000, v126
	v_exp_f32_e32 v69, v69
	v_mul_f32_e32 v73, v73, v78
	v_cvt_pk_bf16_f32 v78, v72, v73
	v_add_f32_e32 v72, 1.0, v74
	v_rcp_f32_e32 v72, v72
	v_add_f32_e32 v73, 1.0, v75
	v_rcp_f32_e32 v73, v73
	v_add_f32_e32 v68, 1.0, v68
	v_rcp_f32_e32 v68, v68
	v_add_f32_e32 v69, 1.0, v69
	v_lshlrev_b32_e32 v74, 16, v127
	v_rcp_f32_e32 v69, v69
	v_mul_f32_e32 v70, 0xbfb8aa3b, v70
	v_mul_f32_e32 v72, v72, v74
	v_and_b32_e32 v74, 0xffff0000, v127
	v_exp_f32_e32 v70, v70
	v_mul_f32_e32 v71, 0xbfb8aa3b, v71
	v_mul_f32_e32 v73, v73, v74
	v_cvt_pk_bf16_f32 v79, v72, v73
	v_lshlrev_b32_e32 v72, 16, v120
	v_exp_f32_e32 v71, v71
	v_mul_f32_e32 v68, v68, v72
	v_and_b32_e32 v72, 0xffff0000, v120
	v_mul_f32_e32 v64, 0xbfb8aa3b, v64
	v_add_u32_e32 v80, 0x18000, v116
	v_mul_f32_e32 v69, v69, v72
	v_exp_f32_e32 v64, v64
	v_mul_f32_e32 v65, 0xbfb8aa3b, v65
	buffer_store_dwordx4 v[76:79], v80, s[24:27], 0 offen sc1
	v_cvt_pk_bf16_f32 v68, v68, v69
	v_add_f32_e32 v69, 1.0, v70
	v_exp_f32_e32 v65, v65
	v_rcp_f32_e32 v69, v69
	v_add_f32_e32 v70, 1.0, v71
	v_rcp_f32_e32 v70, v70
	v_add_f32_e32 v64, 1.0, v64
	v_lshlrev_b32_e32 v71, 16, v121
	v_rcp_f32_e32 v64, v64
	v_add_f32_e32 v65, 1.0, v65
	v_mul_f32_e32 v66, 0xbfb8aa3b, v66
	v_mul_f32_e32 v69, v69, v71
	v_and_b32_e32 v71, 0xffff0000, v121
	v_rcp_f32_e32 v65, v65
	v_exp_f32_e32 v66, v66
	v_mul_f32_e32 v67, 0xbfb8aa3b, v67
	v_mul_f32_e32 v70, v70, v71
	v_exp_f32_e32 v67, v67
	v_cvt_pk_bf16_f32 v69, v69, v70
	v_lshlrev_b32_e32 v70, 16, v122
	v_mul_f32_e32 v64, v64, v70
	v_and_b32_e32 v70, 0xffff0000, v122
	v_mul_f32_e32 v65, v65, v70
	v_cvt_pk_bf16_f32 v70, v64, v65
	v_add_f32_e32 v64, 1.0, v66
	v_rcp_f32_e32 v64, v64
	v_add_f32_e32 v65, 1.0, v67
	v_rcp_f32_e32 v65, v65
	v_lshlrev_b32_e32 v66, 16, v123
	v_mul_f32_e32 v64, v64, v66
	v_and_b32_e32 v66, 0xffff0000, v123
	s_mov_b32 s1, 0x40000
	v_mul_f32_e32 v65, v65, v66
	v_cvt_pk_bf16_f32 v71, v64, v65
	v_add_co_u32_e32 v64, vcc, s1, v150
	buffer_store_dwordx4 v[68:71], v80, s[24:27], 0 offen offset:256 sc1
	s_nop 0
	v_addc_co_u32_e32 v65, vcc, 0, v151, vcc
	global_load_dwordx4 v[88:91], v[64:65], off
	s_mov_b64 s[22:23], 0x40000
	v_lshl_add_u64 v[64:65], v[150:151], 0, s[22:23]
	global_load_dwordx4 v[92:95], v[64:65], off offset:256
	s_mov_b32 s1, 0x48000
	v_add_co_u32_e32 v66, vcc, s1, v150
	s_mov_b64 s[22:23], 0x48000
	s_nop 0
	v_addc_co_u32_e32 v67, vcc, 0, v151, vcc
	v_lshl_add_u64 v[64:65], v[150:151], 0, s[22:23]
	global_load_dwordx4 v[84:87], v[66:67], off
	global_load_dwordx4 v[80:83], v[64:65], off offset:256
	s_mov_b32 s1, 0x50000
	v_mul_f32_e32 v60, 0xbfb8aa3b, v60
	v_mul_f32_e32 v61, 0xbfb8aa3b, v61
	v_add_co_u32_e32 v66, vcc, s1, v150
	v_exp_f32_e32 v60, v60
	v_exp_f32_e32 v61, v61
	s_mov_b64 s[22:23], 0x50000
	v_addc_co_u32_e32 v67, vcc, 0, v151, vcc
	v_lshl_add_u64 v[64:65], v[150:151], 0, s[22:23]
	global_load_dwordx4 v[76:79], v[66:67], off
	global_load_dwordx4 v[72:75], v[64:65], off offset:256
	v_add_f32_e32 v60, 1.0, v60
	v_add_f32_e32 v61, 1.0, v61
	v_rcp_f32_e32 v60, v60
	v_rcp_f32_e32 v61, v61
	v_mul_f32_e32 v62, 0xbfb8aa3b, v62
	v_exp_f32_e32 v62, v62
	v_mul_f32_e32 v63, 0xbfb8aa3b, v63
	s_mov_b32 s1, 0x58000
	v_exp_f32_e32 v63, v63
	s_mov_b64 s[22:23], 0x58000
	v_add_co_u32_e32 v66, vcc, s1, v150
	v_mul_f32_e32 v56, 0xbfb8aa3b, v56
	v_lshl_add_u64 v[64:65], v[150:151], 0, s[22:23]
	v_addc_co_u32_e32 v67, vcc, 0, v151, vcc
	v_exp_f32_e32 v56, v56
	v_mul_f32_e32 v57, 0xbfb8aa3b, v57
	global_load_dwordx4 v[68:71], v[66:67], off
	s_nop 0
	global_load_dwordx4 v[64:67], v[64:65], off offset:256
	v_exp_f32_e32 v57, v57
	v_add_f32_e32 v56, 1.0, v56
	v_rcp_f32_e32 v56, v56
	v_mul_f32_e32 v58, 0xbfb8aa3b, v58
	v_add_f32_e32 v57, 1.0, v57
	v_rcp_f32_e32 v57, v57
	v_exp_f32_e32 v58, v58
	v_mul_f32_e32 v59, 0xbfb8aa3b, v59
	v_exp_f32_e32 v59, v59
	v_mul_f32_e32 v52, 0xbfb8aa3b, v52
	v_exp_f32_e32 v52, v52
	v_mul_f32_e32 v53, 0xbfb8aa3b, v53
	v_exp_f32_e32 v53, v53
	v_mul_f32_e32 v54, 0xbfb8aa3b, v54
	v_add_f32_e32 v52, 1.0, v52
	v_rcp_f32_e32 v52, v52
	v_add_f32_e32 v53, 1.0, v53
	v_rcp_f32_e32 v53, v53
	v_exp_f32_e32 v54, v54
	v_mul_f32_e32 v55, 0xbfb8aa3b, v55
	v_exp_f32_e32 v55, v55
	v_mul_f32_e32 v48, 0xbfb8aa3b, v48
	v_add_u32_e32 v96, 0x40000, v116
	v_exp_f32_e32 v48, v48
	v_mul_f32_e32 v49, 0xbfb8aa3b, v49
	v_exp_f32_e32 v49, v49
	v_mul_f32_e32 v50, 0xbfb8aa3b, v50
	v_add_f32_e32 v48, 1.0, v48
	v_rcp_f32_e32 v48, v48
	v_add_f32_e32 v49, 1.0, v49
	v_rcp_f32_e32 v49, v49
	v_exp_f32_e32 v50, v50
	v_mul_f32_e32 v51, 0xbfb8aa3b, v51
	v_exp_f32_e32 v51, v51
	v_mul_f32_e32 v44, 0xbfb8aa3b, v44
	v_exp_f32_e32 v44, v44
	v_mul_f32_e32 v45, 0xbfb8aa3b, v45
	s_waitcnt vmcnt(0)
	v_lshlrev_b32_e32 v97, 16, v88
	v_and_b32_e32 v88, 0xffff0000, v88
	v_mul_f32_e32 v60, v60, v97
	v_mul_f32_e32 v61, v61, v88
	v_cvt_pk_bf16_f32 v60, v60, v61
	v_add_f32_e32 v61, 1.0, v62
	v_rcp_f32_e32 v61, v61
	v_add_f32_e32 v62, 1.0, v63
	v_rcp_f32_e32 v62, v62
	v_lshlrev_b32_e32 v63, 16, v89
	v_mul_f32_e32 v61, v61, v63
	v_and_b32_e32 v63, 0xffff0000, v89
	v_mul_f32_e32 v62, v62, v63
	v_cvt_pk_bf16_f32 v61, v61, v62
	v_lshlrev_b32_e32 v62, 16, v90
	v_mul_f32_e32 v56, v56, v62
	v_and_b32_e32 v62, 0xffff0000, v90
	v_mul_f32_e32 v57, v57, v62
	v_cvt_pk_bf16_f32 v62, v56, v57
	v_add_f32_e32 v56, 1.0, v58
	v_rcp_f32_e32 v56, v56
	v_add_f32_e32 v57, 1.0, v59
	v_rcp_f32_e32 v57, v57
	v_lshlrev_b32_e32 v58, 16, v91
	v_mul_f32_e32 v56, v56, v58
	v_and_b32_e32 v58, 0xffff0000, v91
	v_mul_f32_e32 v57, v57, v58
	v_cvt_pk_bf16_f32 v63, v56, v57
	v_lshlrev_b32_e32 v56, 16, v92
	v_mul_f32_e32 v52, v52, v56
	v_and_b32_e32 v56, 0xffff0000, v92
	v_mul_f32_e32 v53, v53, v56
	buffer_store_dwordx4 v[60:63], v96, s[24:27], 0 offen sc1
	v_cvt_pk_bf16_f32 v52, v52, v53
	v_add_f32_e32 v53, 1.0, v54
	v_rcp_f32_e32 v53, v53
	v_add_f32_e32 v54, 1.0, v55
	v_rcp_f32_e32 v54, v54
	v_lshlrev_b32_e32 v55, 16, v93
	v_mul_f32_e32 v53, v53, v55
	v_and_b32_e32 v55, 0xffff0000, v93
	v_mul_f32_e32 v54, v54, v55
	v_cvt_pk_bf16_f32 v53, v53, v54
	v_lshlrev_b32_e32 v54, 16, v94
	v_mul_f32_e32 v48, v48, v54
	v_and_b32_e32 v54, 0xffff0000, v94
	v_mul_f32_e32 v49, v49, v54
	v_cvt_pk_bf16_f32 v54, v48, v49
	v_add_f32_e32 v48, 1.0, v50
	v_exp_f32_e32 v45, v45
	v_rcp_f32_e32 v48, v48
	v_add_f32_e32 v49, 1.0, v51
	v_rcp_f32_e32 v49, v49
	v_add_f32_e32 v44, 1.0, v44
	v_lshlrev_b32_e32 v50, 16, v95
	v_rcp_f32_e32 v44, v44
	v_add_f32_e32 v45, 1.0, v45
	v_mul_f32_e32 v48, v48, v50
	v_and_b32_e32 v50, 0xffff0000, v95
	v_rcp_f32_e32 v45, v45
	v_mul_f32_e32 v46, 0xbfb8aa3b, v46
	v_mul_f32_e32 v49, v49, v50
	v_exp_f32_e32 v46, v46
	v_mul_f32_e32 v47, 0xbfb8aa3b, v47
	v_cvt_pk_bf16_f32 v55, v48, v49
	v_lshlrev_b32_e32 v49, 16, v84
	v_exp_f32_e32 v47, v47
	v_mul_f32_e32 v44, v44, v49
	v_and_b32_e32 v49, 0xffff0000, v84
	v_mul_f32_e32 v40, 0xbfb8aa3b, v40
	v_mul_f32_e32 v45, v45, v49
	v_exp_f32_e32 v40, v40
	v_mul_f32_e32 v41, 0xbfb8aa3b, v41
	buffer_store_dwordx4 v[52:55], v96, s[24:27], 0 offen offset:256 sc1
	v_cvt_pk_bf16_f32 v44, v44, v45
	v_add_f32_e32 v45, 1.0, v46
	v_exp_f32_e32 v41, v41
	v_rcp_f32_e32 v45, v45
	v_add_f32_e32 v46, 1.0, v47
	v_rcp_f32_e32 v46, v46
	v_add_f32_e32 v40, 1.0, v40
	v_lshlrev_b32_e32 v47, 16, v85
	v_rcp_f32_e32 v40, v40
	v_add_f32_e32 v41, 1.0, v41
	v_mul_f32_e32 v42, 0xbfb8aa3b, v42
	v_mul_f32_e32 v45, v45, v47
	v_and_b32_e32 v47, 0xffff0000, v85
	v_rcp_f32_e32 v41, v41
	v_exp_f32_e32 v42, v42
	v_mul_f32_e32 v43, 0xbfb8aa3b, v43
	v_mul_f32_e32 v46, v46, v47
	v_exp_f32_e32 v43, v43
	v_mul_f32_e32 v36, 0xbfb8aa3b, v36
	v_cvt_pk_bf16_f32 v45, v45, v46
	v_lshlrev_b32_e32 v46, 16, v86
	v_exp_f32_e32 v36, v36
	v_mul_f32_e32 v37, 0xbfb8aa3b, v37
	v_mul_f32_e32 v40, v40, v46
	v_and_b32_e32 v46, 0xffff0000, v86
	v_exp_f32_e32 v37, v37
	v_mul_f32_e32 v41, v41, v46
	v_cvt_pk_bf16_f32 v46, v40, v41
	v_add_f32_e32 v40, 1.0, v42
	v_rcp_f32_e32 v40, v40
	v_add_f32_e32 v41, 1.0, v43
	v_rcp_f32_e32 v41, v41
	v_add_f32_e32 v36, 1.0, v36
	v_rcp_f32_e32 v36, v36
	v_add_f32_e32 v37, 1.0, v37
	v_lshlrev_b32_e32 v42, 16, v87
	v_rcp_f32_e32 v37, v37
	v_mul_f32_e32 v38, 0xbfb8aa3b, v38
	v_mul_f32_e32 v40, v40, v42
	v_and_b32_e32 v42, 0xffff0000, v87
	v_exp_f32_e32 v38, v38
	v_mul_f32_e32 v39, 0xbfb8aa3b, v39
	v_mul_f32_e32 v41, v41, v42
	v_cvt_pk_bf16_f32 v47, v40, v41
	v_lshlrev_b32_e32 v40, 16, v80
	v_exp_f32_e32 v39, v39
	v_mul_f32_e32 v36, v36, v40
	v_and_b32_e32 v40, 0xffff0000, v80
	v_mul_f32_e32 v32, 0xbfb8aa3b, v32
	v_add_u32_e32 v48, 0x48000, v116
	v_mul_f32_e32 v37, v37, v40
	v_exp_f32_e32 v32, v32
	v_mul_f32_e32 v33, 0xbfb8aa3b, v33
	buffer_store_dwordx4 v[44:47], v48, s[24:27], 0 offen sc1
	v_cvt_pk_bf16_f32 v36, v36, v37
	v_add_f32_e32 v37, 1.0, v38
	v_exp_f32_e32 v33, v33
	v_rcp_f32_e32 v37, v37
	v_add_f32_e32 v38, 1.0, v39
	v_rcp_f32_e32 v38, v38
	v_add_f32_e32 v32, 1.0, v32
	v_lshlrev_b32_e32 v39, 16, v81
	v_rcp_f32_e32 v32, v32
	v_add_f32_e32 v33, 1.0, v33
	v_mul_f32_e32 v34, 0xbfb8aa3b, v34
	v_mul_f32_e32 v37, v37, v39
	v_and_b32_e32 v39, 0xffff0000, v81
	v_rcp_f32_e32 v33, v33
	v_exp_f32_e32 v34, v34
	v_mul_f32_e32 v35, 0xbfb8aa3b, v35
	v_mul_f32_e32 v38, v38, v39
	v_exp_f32_e32 v35, v35
	v_cvt_pk_bf16_f32 v37, v37, v38
	v_lshlrev_b32_e32 v38, 16, v82
	v_mul_f32_e32 v28, 0xbfb8aa3b, v28
	v_mul_f32_e32 v32, v32, v38
	v_and_b32_e32 v38, 0xffff0000, v82
	v_exp_f32_e32 v28, v28
	v_mul_f32_e32 v29, 0xbfb8aa3b, v29
	v_mul_f32_e32 v33, v33, v38
	v_cvt_pk_bf16_f32 v38, v32, v33
	v_add_f32_e32 v32, 1.0, v34
	v_exp_f32_e32 v29, v29
	v_rcp_f32_e32 v32, v32
	v_add_f32_e32 v33, 1.0, v35
	v_rcp_f32_e32 v33, v33
	v_add_f32_e32 v28, 1.0, v28
	v_lshlrev_b32_e32 v34, 16, v83
	v_rcp_f32_e32 v28, v28
	v_add_f32_e32 v29, 1.0, v29
	v_mul_f32_e32 v32, v32, v34
	v_and_b32_e32 v34, 0xffff0000, v83
	v_rcp_f32_e32 v29, v29
	v_mul_f32_e32 v30, 0xbfb8aa3b, v30
	v_mul_f32_e32 v33, v33, v34
	v_exp_f32_e32 v30, v30
	v_mul_f32_e32 v31, 0xbfb8aa3b, v31
	v_cvt_pk_bf16_f32 v39, v32, v33
	v_lshlrev_b32_e32 v33, 16, v76
	v_exp_f32_e32 v31, v31
	v_mul_f32_e32 v28, v28, v33
	v_and_b32_e32 v33, 0xffff0000, v76
	v_mul_f32_e32 v24, 0xbfb8aa3b, v24
	v_mul_f32_e32 v29, v29, v33
	v_exp_f32_e32 v24, v24
	v_mul_f32_e32 v25, 0xbfb8aa3b, v25
	buffer_store_dwordx4 v[36:39], v48, s[24:27], 0 offen offset:256 sc1
	v_cvt_pk_bf16_f32 v28, v28, v29
	v_add_f32_e32 v29, 1.0, v30
	v_exp_f32_e32 v25, v25
	v_rcp_f32_e32 v29, v29
	v_add_f32_e32 v30, 1.0, v31
	v_rcp_f32_e32 v30, v30
	v_add_f32_e32 v24, 1.0, v24
	v_lshlrev_b32_e32 v31, 16, v77
	v_rcp_f32_e32 v24, v24
	v_add_f32_e32 v25, 1.0, v25
	v_mul_f32_e32 v26, 0xbfb8aa3b, v26
	v_mul_f32_e32 v29, v29, v31
	v_and_b32_e32 v31, 0xffff0000, v77
	v_rcp_f32_e32 v25, v25
	v_exp_f32_e32 v26, v26
	v_mul_f32_e32 v27, 0xbfb8aa3b, v27
	v_mul_f32_e32 v30, v30, v31
	v_exp_f32_e32 v27, v27
	v_mul_f32_e32 v20, 0xbfb8aa3b, v20
	v_cvt_pk_bf16_f32 v29, v29, v30
	v_lshlrev_b32_e32 v30, 16, v78
	v_exp_f32_e32 v20, v20
	v_mul_f32_e32 v21, 0xbfb8aa3b, v21
	v_mul_f32_e32 v24, v24, v30
	v_and_b32_e32 v30, 0xffff0000, v78
	v_exp_f32_e32 v21, v21
	v_mul_f32_e32 v25, v25, v30
	v_cvt_pk_bf16_f32 v30, v24, v25
	v_add_f32_e32 v24, 1.0, v26
	v_rcp_f32_e32 v24, v24
	v_add_f32_e32 v25, 1.0, v27
	v_rcp_f32_e32 v25, v25
	v_add_f32_e32 v20, 1.0, v20
	v_rcp_f32_e32 v20, v20
	v_add_f32_e32 v21, 1.0, v21
	v_lshlrev_b32_e32 v26, 16, v79
	v_rcp_f32_e32 v21, v21
	v_mul_f32_e32 v22, 0xbfb8aa3b, v22
	v_mul_f32_e32 v24, v24, v26
	v_and_b32_e32 v26, 0xffff0000, v79
	v_exp_f32_e32 v22, v22
	v_mul_f32_e32 v23, 0xbfb8aa3b, v23
	v_mul_f32_e32 v25, v25, v26
	v_cvt_pk_bf16_f32 v31, v24, v25
	v_lshlrev_b32_e32 v24, 16, v72
	v_exp_f32_e32 v23, v23
	v_mul_f32_e32 v20, v20, v24
	v_and_b32_e32 v24, 0xffff0000, v72
	v_mul_f32_e32 v16, 0xbfb8aa3b, v16
	v_add_u32_e32 v32, 0x50000, v116
	v_mul_f32_e32 v21, v21, v24
	v_exp_f32_e32 v16, v16
	v_mul_f32_e32 v17, 0xbfb8aa3b, v17
	buffer_store_dwordx4 v[28:31], v32, s[24:27], 0 offen sc1
	v_cvt_pk_bf16_f32 v20, v20, v21
	v_add_f32_e32 v21, 1.0, v22
	v_exp_f32_e32 v17, v17
	v_rcp_f32_e32 v21, v21
	v_add_f32_e32 v22, 1.0, v23
	v_rcp_f32_e32 v22, v22
	v_add_f32_e32 v16, 1.0, v16
	v_lshlrev_b32_e32 v23, 16, v73
	v_rcp_f32_e32 v16, v16
	v_add_f32_e32 v17, 1.0, v17
	v_mul_f32_e32 v18, 0xbfb8aa3b, v18
	v_mul_f32_e32 v21, v21, v23
	v_and_b32_e32 v23, 0xffff0000, v73
	v_rcp_f32_e32 v17, v17
	v_exp_f32_e32 v18, v18
	v_mul_f32_e32 v19, 0xbfb8aa3b, v19
	v_mul_f32_e32 v22, v22, v23
	v_exp_f32_e32 v19, v19
	v_cvt_pk_bf16_f32 v21, v21, v22
	v_lshlrev_b32_e32 v22, 16, v74
	v_mul_f32_e32 v12, 0xbfb8aa3b, v12
	v_mul_f32_e32 v16, v16, v22
	v_and_b32_e32 v22, 0xffff0000, v74
	v_exp_f32_e32 v12, v12
	v_mul_f32_e32 v13, 0xbfb8aa3b, v13
	v_mul_f32_e32 v17, v17, v22
	v_cvt_pk_bf16_f32 v22, v16, v17
	v_add_f32_e32 v16, 1.0, v18
	v_exp_f32_e32 v13, v13
	v_rcp_f32_e32 v16, v16
	v_add_f32_e32 v17, 1.0, v19
	v_rcp_f32_e32 v17, v17
	v_add_f32_e32 v12, 1.0, v12
	v_lshlrev_b32_e32 v18, 16, v75
	v_rcp_f32_e32 v12, v12
	v_add_f32_e32 v13, 1.0, v13
	v_mul_f32_e32 v16, v16, v18
	v_and_b32_e32 v18, 0xffff0000, v75
	v_rcp_f32_e32 v13, v13
	v_mul_f32_e32 v14, 0xbfb8aa3b, v14
	v_mul_f32_e32 v17, v17, v18
	v_exp_f32_e32 v14, v14
	v_mul_f32_e32 v15, 0xbfb8aa3b, v15
	v_cvt_pk_bf16_f32 v23, v16, v17
	v_lshlrev_b32_e32 v17, 16, v68
	v_exp_f32_e32 v15, v15
	v_mul_f32_e32 v12, v12, v17
	v_and_b32_e32 v17, 0xffff0000, v68
	v_mul_f32_e32 v8, 0xbfb8aa3b, v8
	v_mul_f32_e32 v13, v13, v17
	v_exp_f32_e32 v8, v8
	v_mul_f32_e32 v9, 0xbfb8aa3b, v9
	buffer_store_dwordx4 v[20:23], v32, s[24:27], 0 offen offset:256 sc1
	v_cvt_pk_bf16_f32 v12, v12, v13
	v_add_f32_e32 v13, 1.0, v14
	v_exp_f32_e32 v9, v9
	v_rcp_f32_e32 v13, v13
	v_add_f32_e32 v14, 1.0, v15
	v_rcp_f32_e32 v14, v14
	v_add_f32_e32 v8, 1.0, v8
	v_lshlrev_b32_e32 v15, 16, v69
	v_rcp_f32_e32 v8, v8
	v_add_f32_e32 v9, 1.0, v9
	v_mul_f32_e32 v10, 0xbfb8aa3b, v10
	v_mul_f32_e32 v13, v13, v15
	v_and_b32_e32 v15, 0xffff0000, v69
	v_rcp_f32_e32 v9, v9
	v_exp_f32_e32 v10, v10
	v_mul_f32_e32 v11, 0xbfb8aa3b, v11
	v_mul_f32_e32 v14, v14, v15
	v_exp_f32_e32 v11, v11
	v_mul_f32_e32 v4, 0xbfb8aa3b, v4
	v_cvt_pk_bf16_f32 v13, v13, v14
	v_lshlrev_b32_e32 v14, 16, v70
	v_exp_f32_e32 v4, v4
	v_mul_f32_e32 v5, 0xbfb8aa3b, v5
	v_mul_f32_e32 v8, v8, v14
	v_and_b32_e32 v14, 0xffff0000, v70
	v_exp_f32_e32 v5, v5
	v_mul_f32_e32 v9, v9, v14
	v_cvt_pk_bf16_f32 v14, v8, v9
	v_add_f32_e32 v8, 1.0, v10
	v_rcp_f32_e32 v8, v8
	v_add_f32_e32 v9, 1.0, v11
	v_rcp_f32_e32 v9, v9
	v_add_f32_e32 v4, 1.0, v4
	v_rcp_f32_e32 v4, v4
	v_add_f32_e32 v5, 1.0, v5
	v_lshlrev_b32_e32 v10, 16, v71
	v_rcp_f32_e32 v5, v5
	v_mul_f32_e32 v6, 0xbfb8aa3b, v6
	v_mul_f32_e32 v8, v8, v10
	v_and_b32_e32 v10, 0xffff0000, v71
	v_exp_f32_e32 v6, v6
	v_mul_f32_e32 v7, 0xbfb8aa3b, v7
	v_mul_f32_e32 v9, v9, v10
	v_cvt_pk_bf16_f32 v15, v8, v9
	v_lshlrev_b32_e32 v8, 16, v64
	v_exp_f32_e32 v7, v7
	v_mul_f32_e32 v4, v4, v8
	v_and_b32_e32 v8, 0xffff0000, v64
	v_mul_f32_e32 v0, 0xbfb8aa3b, v0
	v_add_u32_e32 v16, 0x58000, v116
	v_mul_f32_e32 v5, v5, v8
	v_exp_f32_e32 v0, v0
	v_mul_f32_e32 v1, 0xbfb8aa3b, v1
	buffer_store_dwordx4 v[12:15], v16, s[24:27], 0 offen sc1
	v_cvt_pk_bf16_f32 v4, v4, v5
	v_add_f32_e32 v5, 1.0, v6
	v_exp_f32_e32 v1, v1
	v_rcp_f32_e32 v5, v5
	v_add_f32_e32 v6, 1.0, v7
	v_rcp_f32_e32 v6, v6
	v_add_f32_e32 v0, 1.0, v0
	v_lshlrev_b32_e32 v7, 16, v65
	v_rcp_f32_e32 v0, v0
	v_add_f32_e32 v1, 1.0, v1
	v_mul_f32_e32 v2, 0xbfb8aa3b, v2
	v_mul_f32_e32 v5, v5, v7
	v_and_b32_e32 v7, 0xffff0000, v65
	v_rcp_f32_e32 v1, v1
	v_exp_f32_e32 v2, v2
	v_mul_f32_e32 v3, 0xbfb8aa3b, v3
	v_mul_f32_e32 v6, v6, v7
	v_exp_f32_e32 v3, v3
	v_cvt_pk_bf16_f32 v5, v5, v6
	v_lshlrev_b32_e32 v6, 16, v66
	v_mul_f32_e32 v0, v0, v6
	v_and_b32_e32 v6, 0xffff0000, v66
	v_mul_f32_e32 v1, v1, v6
	v_cvt_pk_bf16_f32 v6, v0, v1
	v_add_f32_e32 v0, 1.0, v2
	v_rcp_f32_e32 v0, v0
	v_add_f32_e32 v1, 1.0, v3
	v_rcp_f32_e32 v1, v1
	v_lshlrev_b32_e32 v2, 16, v67
	v_mul_f32_e32 v0, v0, v2
	v_and_b32_e32 v2, 0xffff0000, v67
	s_and_b64 vcc, exec, s[6:7]
	s_mov_b32 s66, s10
	s_mov_b32 s20, s12
	s_mov_b64 s[58:59], s[18:19]
	s_mov_b64 s[22:23], s[16:17]
	v_mul_f32_e32 v1, v1, v2
	v_cvt_pk_bf16_f32 v7, v0, v1
	buffer_store_dwordx4 v[4:7], v16, s[24:27], 0 offen offset:256 sc1
	s_cbranch_vccz .LBB0_42
	s_waitcnt vmcnt(0)
	s_cmpk_gt_u32 s4, 0xff
	s_cbranch_scc1 .LBB0_53
	s_barrier

.LBB0_161:
	s_ashr_i32 s13, s12, 31
	v_cmp_lt_i64_e32 vcc, s[16:17], v[162:163]
	s_lshl_b64 s[16:17], s[12:13], 19
	s_add_u32 s16, s96, s16
	s_addc_u32 s17, s97, s17
	s_and_b64 s[18:19], vcc, exec
	s_cselect_b32 s9, s17, s23
	s_cselect_b32 s13, s16, s22
	s_ashr_i32 s11, s10, 31
	s_lshl_b64 s[18:19], s[10:11], 19
	s_add_u32 s18, s35, s18
	s_addc_u32 s19, s39, s19
	s_and_b64 s[62:63], vcc, exec
	s_cselect_b32 s11, s19, s59
	s_cselect_b32 s21, s18, s58
	s_add_u32 s22, s22, 0x40080
	s_addc_u32 s23, s23, 0
	s_add_u32 s68, s58, 0x100
	s_addc_u32 s69, s59, 0
	s_mov_b32 s72, -2
	s_add_u32 s2, s22, 0xfffc0080
	s_addc_u32 s15, s23, -1
	s_add_i32 s73, 0, 0x10000
	v_add_u32_e32 v138, s73, v142
	ds_read_b128 v[146:149], v138
	ds_read_b128 v[150:153], v138 offset:1024
	ds_read_b128 v[166:169], v138 offset:2048
	ds_read_b128 v[170:173], v138 offset:3072
	s_cmp_eq_u32 s72, 12
	s_cselect_b32 s63, s9, s15
	s_cselect_b32 s62, s13, s2
	s_cselect_b32 s59, s11, s69
	s_cselect_b32 s58, s21, s68
	v_lshl_add_u64 v[138:139], s[22:23], 0, v[134:135]
	s_add_i32 m0, s43, 0xc000
	ds_read_b128 v[174:177], v145
	ds_read_b128 v[178:181], v145 offset:1024
	ds_read_b128 v[182:185], v145 offset:2048
	ds_read_b128 v[186:189], v145 offset:3072
	ds_read_b128 v[214:217], v145 offset:4096
	ds_read_b128 v[218:221], v145 offset:5120
	ds_read_b128 v[222:225], v145 offset:6144
	ds_read_b128 v[226:229], v145 offset:7168
	global_load_lds_dwordx4 v[138:139], off
	v_lshl_add_u64 v[138:139], s[22:23], 0, v[136:137]
	s_add_i32 m0, s43, 0xe000
	s_nop 0
	global_load_lds_dwordx4 v[138:139], off
	s_waitcnt lgkmcnt(8)
	s_barrier
	s_waitcnt lgkmcnt(0)
	s_setprio 1
	s_waitcnt lgkmcnt(0)
	v_mfma_f32_16x16x32_bf16 v[124:127], v[146:149], v[174:177], 0
	v_mfma_f32_16x16x32_bf16 v[120:123], v[166:169], v[174:177], 0
	v_mfma_f32_16x16x32_bf16 v[108:111], v[146:149], v[182:185], 0
	v_mfma_f32_16x16x32_bf16 v[104:107], v[166:169], v[182:185], 0
	v_mfma_f32_16x16x32_bf16 v[92:95], v[146:149], v[214:217], 0
	v_mfma_f32_16x16x32_bf16 v[88:91], v[166:169], v[214:217], 0
	v_mfma_f32_16x16x32_bf16 v[76:79], v[146:149], v[222:225], 0
	v_mfma_f32_16x16x32_bf16 v[72:75], v[166:169], v[222:225], 0
	v_mfma_f32_16x16x32_bf16 v[124:127], v[150:153], v[178:181], v[124:127]
	v_mfma_f32_16x16x32_bf16 v[120:123], v[170:173], v[178:181], v[120:123]
	v_mfma_f32_16x16x32_bf16 v[108:111], v[150:153], v[186:189], v[108:111]
	v_mfma_f32_16x16x32_bf16 v[104:107], v[170:173], v[186:189], v[104:107]
	v_mfma_f32_16x16x32_bf16 v[92:95], v[150:153], v[218:221], v[92:95]
	v_mfma_f32_16x16x32_bf16 v[88:91], v[170:173], v[218:221], v[88:91]
	v_mfma_f32_16x16x32_bf16 v[76:79], v[150:153], v[226:229], v[76:79]
	v_mfma_f32_16x16x32_bf16 v[72:75], v[170:173], v[226:229], v[72:75]
	s_setprio 0
	s_barrier
	s_add_i32 s2, 0, 0x14000
	v_add_u32_e32 v138, s2, v142
	s_add_i32 s15, s73, s31
	ds_read_b128 v[230:233], v138
	ds_read_b128 v[234:237], v138 offset:1024
	ds_read_b128 v[238:241], v138 offset:2048
	ds_read_b128 v[242:245], v138 offset:3072
	v_lshl_add_u64 v[138:139], s[58:59], 0, v[158:159]
	s_mov_b32 m0, s15
	v_lshl_add_u64 v[154:155], s[58:59], 0, v[132:133]
	global_load_lds_dwordx4 v[138:139], off
	s_add_i32 m0, s15, 0x2000
	s_nop 0
	global_load_lds_dwordx4 v[154:155], off
	s_barrier
	s_waitcnt lgkmcnt(0)
	s_setprio 1
	s_waitcnt lgkmcnt(0)
	v_mfma_f32_16x16x32_bf16 v[116:119], v[230:233], v[174:177], 0
	v_mfma_f32_16x16x32_bf16 v[112:115], v[238:241], v[174:177], 0
	v_mfma_f32_16x16x32_bf16 v[100:103], v[230:233], v[182:185], 0
	v_mfma_f32_16x16x32_bf16 v[96:99], v[238:241], v[182:185], 0
	v_mfma_f32_16x16x32_bf16 v[84:87], v[230:233], v[214:217], 0
	v_mfma_f32_16x16x32_bf16 v[80:83], v[238:241], v[214:217], 0
	v_mfma_f32_16x16x32_bf16 v[68:71], v[230:233], v[222:225], 0
	v_mfma_f32_16x16x32_bf16 v[64:67], v[238:241], v[222:225], 0
	v_mfma_f32_16x16x32_bf16 v[116:119], v[234:237], v[178:181], v[116:119]
	v_mfma_f32_16x16x32_bf16 v[112:115], v[242:245], v[178:181], v[112:115]
	v_mfma_f32_16x16x32_bf16 v[100:103], v[234:237], v[186:189], v[100:103]
	v_mfma_f32_16x16x32_bf16 v[96:99], v[242:245], v[186:189], v[96:99]
	v_mfma_f32_16x16x32_bf16 v[84:87], v[234:237], v[218:221], v[84:87]
	v_mfma_f32_16x16x32_bf16 v[80:83], v[242:245], v[218:221], v[80:83]
	v_mfma_f32_16x16x32_bf16 v[68:71], v[234:237], v[226:229], v[68:71]
	v_mfma_f32_16x16x32_bf16 v[64:67], v[242:245], v[226:229], v[64:67]
	s_setprio 0
	s_mov_b32 m0, s43
	v_lshl_add_u64 v[190:191], s[62:63], 0, v[128:129]
	s_barrier
	ds_read_b128 v[174:177], v145 offset:16384
	ds_read_b128 v[178:181], v145 offset:17408
	ds_read_b128 v[182:185], v145 offset:18432
	ds_read_b128 v[186:189], v145 offset:19456
	ds_read_b128 v[214:217], v145 offset:20480
	ds_read_b128 v[218:221], v145 offset:21504
	ds_read_b128 v[222:225], v145 offset:22528
	ds_read_b128 v[226:229], v145 offset:23552
	global_load_lds_dwordx4 v[190:191], off
	v_lshl_add_u64 v[202:203], s[62:63], 0, v[130:131]
	s_mov_b32 m0, s47
	s_nop 0
	global_load_lds_dwordx4 v[202:203], off
	s_barrier
	s_waitcnt lgkmcnt(0)
	s_setprio 1
	s_waitcnt lgkmcnt(0)
	v_mfma_f32_16x16x32_bf16 v[60:63], v[146:149], v[174:177], 0
	v_mfma_f32_16x16x32_bf16 v[56:59], v[166:169], v[174:177], 0
	v_mfma_f32_16x16x32_bf16 v[44:47], v[146:149], v[182:185], 0
	v_mfma_f32_16x16x32_bf16 v[40:43], v[166:169], v[182:185], 0
	v_mfma_f32_16x16x32_bf16 v[28:31], v[146:149], v[214:217], 0
	v_mfma_f32_16x16x32_bf16 v[24:27], v[166:169], v[214:217], 0
	v_mfma_f32_16x16x32_bf16 v[12:15], v[146:149], v[222:225], 0
	v_mfma_f32_16x16x32_bf16 v[8:11], v[166:169], v[222:225], 0
	v_mfma_f32_16x16x32_bf16 v[60:63], v[150:153], v[178:181], v[60:63]
	v_mfma_f32_16x16x32_bf16 v[56:59], v[170:173], v[178:181], v[56:59]
	v_mfma_f32_16x16x32_bf16 v[44:47], v[150:153], v[186:189], v[44:47]
	v_mfma_f32_16x16x32_bf16 v[40:43], v[170:173], v[186:189], v[40:43]
	v_mfma_f32_16x16x32_bf16 v[28:31], v[150:153], v[218:221], v[28:31]
	v_mfma_f32_16x16x32_bf16 v[24:27], v[170:173], v[218:221], v[24:27]
	v_mfma_f32_16x16x32_bf16 v[12:15], v[150:153], v[226:229], v[12:15]
	v_mfma_f32_16x16x32_bf16 v[8:11], v[170:173], v[226:229], v[8:11]
	s_setprio 0
	s_barrier
	s_add_u32 s74, s58, 0x40000
	s_addc_u32 s75, s59, 0
	s_add_i32 s2, s2, s31
	v_lshl_add_u64 v[146:147], s[74:75], 0, v[158:159]
	s_mov_b32 m0, s2
	s_nop 0
	global_load_lds_dwordx4 v[146:147], off
	v_lshl_add_u64 v[146:147], s[74:75], 0, v[132:133]
	s_add_i32 m0, s2, 0x2000
	s_nop 0
	global_load_lds_dwordx4 v[146:147], off
	s_waitcnt vmcnt(6)
	s_barrier
	s_setprio 1
	v_mfma_f32_16x16x32_bf16 v[52:55], v[230:233], v[174:177], 0
	v_mfma_f32_16x16x32_bf16 v[48:51], v[238:241], v[174:177], 0
	v_mfma_f32_16x16x32_bf16 v[36:39], v[230:233], v[182:185], 0
	v_mfma_f32_16x16x32_bf16 v[32:35], v[238:241], v[182:185], 0
	v_mfma_f32_16x16x32_bf16 v[20:23], v[230:233], v[214:217], 0
	v_mfma_f32_16x16x32_bf16 v[16:19], v[238:241], v[214:217], 0
	v_mfma_f32_16x16x32_bf16 v[4:7], v[230:233], v[222:225], 0
	v_mfma_f32_16x16x32_bf16 v[0:3], v[238:241], v[222:225], 0
	v_mfma_f32_16x16x32_bf16 v[52:55], v[234:237], v[178:181], v[52:55]
	v_mfma_f32_16x16x32_bf16 v[48:51], v[242:245], v[178:181], v[48:51]
	v_mfma_f32_16x16x32_bf16 v[36:39], v[234:237], v[186:189], v[36:39]
	v_mfma_f32_16x16x32_bf16 v[32:35], v[242:245], v[186:189], v[32:35]
	v_mfma_f32_16x16x32_bf16 v[20:23], v[234:237], v[218:221], v[20:23]
	v_mfma_f32_16x16x32_bf16 v[16:19], v[242:245], v[218:221], v[16:19]
	v_mfma_f32_16x16x32_bf16 v[4:7], v[234:237], v[226:229], v[4:7]
	v_mfma_f32_16x16x32_bf16 v[0:3], v[242:245], v[226:229], v[0:3]
	s_setprio 0
	s_add_i32 s2, 0, 0x18000
	v_add_u32_e32 v140, s2, v142
	s_barrier
	ds_read_b128 v[146:149], v140
	ds_read_b128 v[150:153], v140 offset:1024
	ds_read_b128 v[166:169], v140 offset:2048
	ds_read_b128 v[170:173], v140 offset:3072
	s_add_u32 s62, s62, 0x40000
	s_addc_u32 s63, s63, 0
	s_mov_b32 m0, s48
	v_lshl_add_u64 v[204:205], s[62:63], 0, v[128:129]
	ds_read_b128 v[174:177], v145 offset:32768
	ds_read_b128 v[178:181], v145 offset:33792
	ds_read_b128 v[182:185], v145 offset:34816
	ds_read_b128 v[186:189], v145 offset:35840
	ds_read_b128 v[214:217], v145 offset:36864
	ds_read_b128 v[218:221], v145 offset:37888
	ds_read_b128 v[222:225], v145 offset:38912
	ds_read_b128 v[226:229], v145 offset:39936
	global_load_lds_dwordx4 v[204:205], off
	v_lshl_add_u64 v[204:205], s[62:63], 0, v[130:131]
	s_mov_b32 m0, s50
	s_nop 0
	global_load_lds_dwordx4 v[204:205], off
	s_waitcnt lgkmcnt(8)
	s_barrier
	s_waitcnt lgkmcnt(0)
	s_setprio 1
	s_waitcnt lgkmcnt(0)
	v_mfma_f32_16x16x32_bf16 v[124:127], v[146:149], v[174:177], v[124:127]
	v_mfma_f32_16x16x32_bf16 v[120:123], v[166:169], v[174:177], v[120:123]
	v_mfma_f32_16x16x32_bf16 v[108:111], v[146:149], v[182:185], v[108:111]
	v_mfma_f32_16x16x32_bf16 v[104:107], v[166:169], v[182:185], v[104:107]
	v_mfma_f32_16x16x32_bf16 v[92:95], v[146:149], v[214:217], v[92:95]
	v_mfma_f32_16x16x32_bf16 v[88:91], v[166:169], v[214:217], v[88:91]
	v_mfma_f32_16x16x32_bf16 v[76:79], v[146:149], v[222:225], v[76:79]
	v_mfma_f32_16x16x32_bf16 v[72:75], v[166:169], v[222:225], v[72:75]
	v_mfma_f32_16x16x32_bf16 v[124:127], v[150:153], v[178:181], v[124:127]
	v_mfma_f32_16x16x32_bf16 v[120:123], v[170:173], v[178:181], v[120:123]
	v_mfma_f32_16x16x32_bf16 v[108:111], v[150:153], v[186:189], v[108:111]
	v_mfma_f32_16x16x32_bf16 v[104:107], v[170:173], v[186:189], v[104:107]
	v_mfma_f32_16x16x32_bf16 v[92:95], v[150:153], v[218:221], v[92:95]
	v_mfma_f32_16x16x32_bf16 v[88:91], v[170:173], v[218:221], v[88:91]
	v_mfma_f32_16x16x32_bf16 v[76:79], v[150:153], v[226:229], v[76:79]
	v_mfma_f32_16x16x32_bf16 v[72:75], v[170:173], v[226:229], v[72:75]
	s_setprio 0
	s_barrier
	s_add_i32 s15, 0, 0x1c000
	s_add_i32 s2, s2, s31
	v_add_u32_e32 v140, s15, v142
	v_lshl_add_u64 v[138:139], v[138:139], 0, s[70:71]
	s_mov_b32 m0, s2
	ds_read_b128 v[230:233], v140
	ds_read_b128 v[234:237], v140 offset:1024
	ds_read_b128 v[238:241], v140 offset:2048
	ds_read_b128 v[242:245], v140 offset:3072
	global_load_lds_dwordx4 v[138:139], off
	v_lshl_add_u64 v[138:139], v[154:155], 0, s[70:71]
	s_add_i32 m0, s2, 0x2000
	s_nop 0
	global_load_lds_dwordx4 v[138:139], off
	s_barrier
	s_waitcnt lgkmcnt(0)
	s_setprio 1
	s_waitcnt lgkmcnt(0)
	v_mfma_f32_16x16x32_bf16 v[116:119], v[230:233], v[174:177], v[116:119]
	v_mfma_f32_16x16x32_bf16 v[112:115], v[238:241], v[174:177], v[112:115]
	v_mfma_f32_16x16x32_bf16 v[100:103], v[230:233], v[182:185], v[100:103]
	v_mfma_f32_16x16x32_bf16 v[96:99], v[238:241], v[182:185], v[96:99]
	v_mfma_f32_16x16x32_bf16 v[84:87], v[230:233], v[214:217], v[84:87]
	v_mfma_f32_16x16x32_bf16 v[80:83], v[238:241], v[214:217], v[80:83]
	v_mfma_f32_16x16x32_bf16 v[68:71], v[230:233], v[222:225], v[68:71]
	v_mfma_f32_16x16x32_bf16 v[64:67], v[238:241], v[222:225], v[64:67]
	v_mfma_f32_16x16x32_bf16 v[116:119], v[234:237], v[178:181], v[116:119]
	v_mfma_f32_16x16x32_bf16 v[112:115], v[242:245], v[178:181], v[112:115]
	v_mfma_f32_16x16x32_bf16 v[100:103], v[234:237], v[186:189], v[100:103]
	v_mfma_f32_16x16x32_bf16 v[96:99], v[242:245], v[186:189], v[96:99]
	v_mfma_f32_16x16x32_bf16 v[84:87], v[234:237], v[218:221], v[84:87]
	v_mfma_f32_16x16x32_bf16 v[80:83], v[242:245], v[218:221], v[80:83]
	v_mfma_f32_16x16x32_bf16 v[68:71], v[234:237], v[226:229], v[68:71]
	v_mfma_f32_16x16x32_bf16 v[64:67], v[242:245], v[226:229], v[64:67]
	s_setprio 0
	s_mov_b32 m0, s51
	v_lshl_add_u64 v[138:139], v[190:191], 0, s[70:71]
	s_barrier
	ds_read_b128 v[174:177], v145 offset:49152
	ds_read_b128 v[178:181], v145 offset:50176
	ds_read_b128 v[182:185], v145 offset:51200
	ds_read_b128 v[186:189], v145 offset:52224
	ds_read_b128 v[214:217], v145 offset:53248
	ds_read_b128 v[218:221], v145 offset:54272
	ds_read_b128 v[222:225], v145 offset:55296
	ds_read_b128 v[226:229], v145 offset:56320
	global_load_lds_dwordx4 v[138:139], off
	v_lshl_add_u64 v[138:139], v[202:203], 0, s[70:71]
	s_mov_b32 m0, s65
	s_nop 0
	global_load_lds_dwordx4 v[138:139], off
	s_barrier
	s_waitcnt lgkmcnt(0)
	s_setprio 1
	s_waitcnt lgkmcnt(0)
	v_mfma_f32_16x16x32_bf16 v[60:63], v[146:149], v[174:177], v[60:63]
	v_mfma_f32_16x16x32_bf16 v[56:59], v[166:169], v[174:177], v[56:59]
	v_mfma_f32_16x16x32_bf16 v[44:47], v[146:149], v[182:185], v[44:47]
	v_mfma_f32_16x16x32_bf16 v[40:43], v[166:169], v[182:185], v[40:43]
	v_mfma_f32_16x16x32_bf16 v[28:31], v[146:149], v[214:217], v[28:31]
	v_mfma_f32_16x16x32_bf16 v[24:27], v[166:169], v[214:217], v[24:27]
	v_mfma_f32_16x16x32_bf16 v[12:15], v[146:149], v[222:225], v[12:15]
	v_mfma_f32_16x16x32_bf16 v[8:11], v[166:169], v[222:225], v[8:11]
	v_mfma_f32_16x16x32_bf16 v[60:63], v[150:153], v[178:181], v[60:63]
	v_mfma_f32_16x16x32_bf16 v[56:59], v[170:173], v[178:181], v[56:59]
	v_mfma_f32_16x16x32_bf16 v[44:47], v[150:153], v[186:189], v[44:47]
	v_mfma_f32_16x16x32_bf16 v[40:43], v[170:173], v[186:189], v[40:43]
	v_mfma_f32_16x16x32_bf16 v[28:31], v[150:153], v[218:221], v[28:31]
	v_mfma_f32_16x16x32_bf16 v[24:27], v[170:173], v[218:221], v[24:27]
	v_mfma_f32_16x16x32_bf16 v[12:15], v[150:153], v[226:229], v[12:15]
	v_mfma_f32_16x16x32_bf16 v[8:11], v[170:173], v[226:229], v[8:11]
	s_setprio 0
	s_barrier
	s_add_u32 s58, s58, 0x40080
	s_addc_u32 s59, s59, 0
	s_add_i32 s2, s15, s31
	v_lshl_add_u64 v[138:139], s[58:59], 0, v[158:159]
	s_mov_b32 m0, s2
	s_nop 0
	global_load_lds_dwordx4 v[138:139], off
	v_lshl_add_u64 v[138:139], s[58:59], 0, v[132:133]
	s_add_i32 m0, s2, 0x2000
	s_nop 0
	global_load_lds_dwordx4 v[138:139], off
	s_waitcnt vmcnt(6)
	s_barrier
	s_setprio 1
	v_mfma_f32_16x16x32_bf16 v[52:55], v[230:233], v[174:177], v[52:55]
	v_mfma_f32_16x16x32_bf16 v[48:51], v[238:241], v[174:177], v[48:51]
	v_mfma_f32_16x16x32_bf16 v[36:39], v[230:233], v[182:185], v[36:39]
	v_mfma_f32_16x16x32_bf16 v[32:35], v[238:241], v[182:185], v[32:35]
	v_mfma_f32_16x16x32_bf16 v[20:23], v[230:233], v[214:217], v[20:23]
	v_mfma_f32_16x16x32_bf16 v[16:19], v[238:241], v[214:217], v[16:19]
	v_mfma_f32_16x16x32_bf16 v[4:7], v[230:233], v[222:225], v[4:7]
	v_mfma_f32_16x16x32_bf16 v[0:3], v[238:241], v[222:225], v[0:3]
	v_mfma_f32_16x16x32_bf16 v[52:55], v[234:237], v[178:181], v[52:55]
	v_mfma_f32_16x16x32_bf16 v[48:51], v[242:245], v[178:181], v[48:51]
	v_mfma_f32_16x16x32_bf16 v[36:39], v[234:237], v[186:189], v[36:39]
	v_mfma_f32_16x16x32_bf16 v[32:35], v[242:245], v[186:189], v[32:35]
	v_mfma_f32_16x16x32_bf16 v[20:23], v[234:237], v[218:221], v[20:23]
	v_mfma_f32_16x16x32_bf16 v[16:19], v[242:245], v[218:221], v[16:19]
	v_mfma_f32_16x16x32_bf16 v[4:7], v[234:237], v[226:229], v[4:7]
	v_mfma_f32_16x16x32_bf16 v[0:3], v[242:245], v[226:229], v[0:3]
	s_setprio 0
	s_add_i32 s72, s72, 2
	s_add_u32 s22, s22, 0x100
	s_addc_u32 s23, s23, 0
	s_add_u32 s68, s68, 0x100
	s_addc_u32 s69, s69, 0
	s_cmp_gt_u32 s72, 13
	s_barrier
	s_cbranch_scc1 .Lzp_exit1

.Lzp_exit1:
	s_lshl_b32 s11, s20, 8
	s_cmp_lg_u32 s20, s4
	s_cselect_b64 s[20:21], -1, 0
	v_add_u32_e32 v138, s11, v141
	s_mov_b64 s[22:23], -1
	s_and_b64 vcc, exec, s[20:21]
	s_cbranch_vccz .LBB0_165
	v_ashrrev_i32_e32 v139, 31, v138
	v_lshlrev_b64 v[146:147], 6, v[138:139]
	v_lshl_add_u64 v[154:155], s[94:95], 0, v[146:147]
	global_load_dwordx4 v[146:149], v[154:155], off offset:48
	global_load_dwordx4 v[150:153], v[154:155], off offset:32
	global_load_dwordx4 v[166:169], v[154:155], off offset:16
	global_load_dwordx4 v[170:173], v[154:155], off
	s_mov_b64 s[22:23], 0
	s_waitcnt vmcnt(0)
	v_add_f32_e32 v150, v150, v151
	v_add_f32_e32 v152, v152, v153
	v_mov_b32_e32 v154, v171
	v_mov_b32_e32 v155, v172
	v_mov_b32_e32 v171, v173
	v_pk_add_f32 v[154:155], v[154:155], v[170:171]
	v_mov_b32_e32 v170, v167
	v_mov_b32_e32 v171, v168
	v_mov_b32_e32 v167, v169
	v_pk_add_f32 v[166:167], v[170:171], v[166:167]
	v_pk_add_f32 v[154:155], v[154:155], v[154:155] op_sel:[0,1] op_sel_hi:[1,0]
	v_pk_add_f32 v[166:167], v[166:167], v[166:167] op_sel:[0,1] op_sel_hi:[1,0]
	v_mov_b32_e32 v155, v146
	v_mov_b32_e32 v167, v147
	v_mov_b32_e32 v151, v148
	v_mov_b32_e32 v153, v149
	v_pk_add_f32 v[146:147], v[154:155], v[166:167]
	v_pk_add_f32 v[148:149], v[150:151], v[152:153]
	s_nop 0
	v_pk_add_f32 v[146:147], v[146:147], v[148:149]
	s_nop 0
	v_add_f32_e32 v139, v146, v147
	v_fmamk_f32 v139, v139, 0x3a800000, v193
	v_cmp_gt_f32_e32 vcc, s40, v139
	v_mul_f32_e32 v140, 0x4b800000, v139
	s_nop 0
	v_cndmask_b32_e32 v139, v139, v140, vcc
	v_rsq_f32_e32 v139, v139
	s_nop 0
	v_mul_f32_e32 v140, 0x45800000, v139
	v_cndmask_b32_e32 v140, v139, v140, vcc

.LBB0_533:
	v_mov_b64_e32 v[0:1], 0x300
	s_ashr_i32 s17, s16, 31
	v_cmp_lt_i64_e32 vcc, s[18:19], v[0:1]
	s_lshl_b64 s[18:19], s[16:17], 19
	s_add_u32 s18, s96, s18
	s_addc_u32 s19, s97, s19
	s_and_b64 s[20:21], vcc, exec
	s_cselect_b32 s9, s19, s25
	s_cselect_b32 s17, s18, s24
	s_ashr_i32 s11, s10, 31
	s_lshl_b64 s[20:21], s[10:11], 19
	s_add_u32 s20, s35, s20
	s_addc_u32 s21, s39, s21
	s_and_b64 s[62:63], vcc, exec
	s_cselect_b32 s11, s21, s59
	s_cselect_b32 s23, s20, s58
	s_add_u32 s24, s24, 0x40080
	s_addc_u32 s25, s25, 0
	s_add_u32 s68, s58, 0x100
	s_addc_u32 s69, s59, 0
	s_mov_b32 s72, -2
	s_add_u32 s2, s24, 0xfffc0080
	s_addc_u32 s15, s25, -1
	s_add_i32 s73, 0, 0x10000
	v_add_u32_e32 v138, s73, v142
	ds_read_b128 v[146:149], v138
	ds_read_b128 v[150:153], v138 offset:1024
	ds_read_b128 v[166:169], v138 offset:2048
	ds_read_b128 v[170:173], v138 offset:3072
	s_cmp_eq_u32 s72, 12
	s_cselect_b32 s63, s9, s15
	s_cselect_b32 s62, s17, s2
	s_cselect_b32 s59, s11, s69
	s_cselect_b32 s58, s23, s68
	v_lshl_add_u64 v[138:139], s[24:25], 0, v[134:135]
	s_add_i32 m0, s43, 0xc000
	ds_read_b128 v[174:177], v145
	ds_read_b128 v[178:181], v145 offset:1024
	ds_read_b128 v[182:185], v145 offset:2048
	ds_read_b128 v[186:189], v145 offset:3072
	ds_read_b128 v[214:217], v145 offset:4096
	ds_read_b128 v[218:221], v145 offset:5120
	ds_read_b128 v[222:225], v145 offset:6144
	ds_read_b128 v[226:229], v145 offset:7168
	global_load_lds_dwordx4 v[138:139], off
	v_lshl_add_u64 v[138:139], s[24:25], 0, v[136:137]
	s_add_i32 m0, s43, 0xe000
	s_nop 0
	global_load_lds_dwordx4 v[138:139], off
	s_waitcnt lgkmcnt(8)
	s_barrier
	s_waitcnt lgkmcnt(0)
	s_setprio 1
	s_waitcnt lgkmcnt(0)
	v_mfma_f32_16x16x32_bf16 v[124:127], v[146:149], v[174:177], 0
	v_mfma_f32_16x16x32_bf16 v[120:123], v[166:169], v[174:177], 0
	v_mfma_f32_16x16x32_bf16 v[108:111], v[146:149], v[182:185], 0
	v_mfma_f32_16x16x32_bf16 v[104:107], v[166:169], v[182:185], 0
	v_mfma_f32_16x16x32_bf16 v[92:95], v[146:149], v[214:217], 0
	v_mfma_f32_16x16x32_bf16 v[88:91], v[166:169], v[214:217], 0
	v_mfma_f32_16x16x32_bf16 v[76:79], v[146:149], v[222:225], 0
	v_mfma_f32_16x16x32_bf16 v[72:75], v[166:169], v[222:225], 0
	v_mfma_f32_16x16x32_bf16 v[124:127], v[150:153], v[178:181], v[124:127]
	v_mfma_f32_16x16x32_bf16 v[120:123], v[170:173], v[178:181], v[120:123]
	v_mfma_f32_16x16x32_bf16 v[108:111], v[150:153], v[186:189], v[108:111]
	v_mfma_f32_16x16x32_bf16 v[104:107], v[170:173], v[186:189], v[104:107]
	v_mfma_f32_16x16x32_bf16 v[92:95], v[150:153], v[218:221], v[92:95]
	v_mfma_f32_16x16x32_bf16 v[88:91], v[170:173], v[218:221], v[88:91]
	v_mfma_f32_16x16x32_bf16 v[76:79], v[150:153], v[226:229], v[76:79]
	v_mfma_f32_16x16x32_bf16 v[72:75], v[170:173], v[226:229], v[72:75]
	s_setprio 0
	s_barrier
	s_add_i32 s2, 0, 0x14000
	v_add_u32_e32 v138, s2, v142
	s_add_i32 s15, s73, s31
	ds_read_b128 v[230:233], v138
	ds_read_b128 v[234:237], v138 offset:1024
	ds_read_b128 v[238:241], v138 offset:2048
	ds_read_b128 v[242:245], v138 offset:3072
	v_lshl_add_u64 v[138:139], s[58:59], 0, v[158:159]
	s_mov_b32 m0, s15
	v_lshl_add_u64 v[154:155], s[58:59], 0, v[132:133]
	global_load_lds_dwordx4 v[138:139], off
	s_add_i32 m0, s15, 0x2000
	s_nop 0
	global_load_lds_dwordx4 v[154:155], off
	s_barrier
	s_waitcnt lgkmcnt(0)
	s_setprio 1
	s_waitcnt lgkmcnt(0)
	v_mfma_f32_16x16x32_bf16 v[116:119], v[230:233], v[174:177], 0
	v_mfma_f32_16x16x32_bf16 v[112:115], v[238:241], v[174:177], 0
	v_mfma_f32_16x16x32_bf16 v[100:103], v[230:233], v[182:185], 0
	v_mfma_f32_16x16x32_bf16 v[96:99], v[238:241], v[182:185], 0
	v_mfma_f32_16x16x32_bf16 v[84:87], v[230:233], v[214:217], 0
	v_mfma_f32_16x16x32_bf16 v[80:83], v[238:241], v[214:217], 0
	v_mfma_f32_16x16x32_bf16 v[68:71], v[230:233], v[222:225], 0
	v_mfma_f32_16x16x32_bf16 v[64:67], v[238:241], v[222:225], 0
	v_mfma_f32_16x16x32_bf16 v[116:119], v[234:237], v[178:181], v[116:119]
	v_mfma_f32_16x16x32_bf16 v[112:115], v[242:245], v[178:181], v[112:115]
	v_mfma_f32_16x16x32_bf16 v[100:103], v[234:237], v[186:189], v[100:103]
	v_mfma_f32_16x16x32_bf16 v[96:99], v[242:245], v[186:189], v[96:99]
	v_mfma_f32_16x16x32_bf16 v[84:87], v[234:237], v[218:221], v[84:87]
	v_mfma_f32_16x16x32_bf16 v[80:83], v[242:245], v[218:221], v[80:83]
	v_mfma_f32_16x16x32_bf16 v[68:71], v[234:237], v[226:229], v[68:71]
	v_mfma_f32_16x16x32_bf16 v[64:67], v[242:245], v[226:229], v[64:67]
	s_setprio 0
	s_mov_b32 m0, s43
	v_lshl_add_u64 v[190:191], s[62:63], 0, v[128:129]
	s_barrier
	ds_read_b128 v[174:177], v145 offset:16384
	ds_read_b128 v[178:181], v145 offset:17408
	ds_read_b128 v[182:185], v145 offset:18432
	ds_read_b128 v[186:189], v145 offset:19456
	ds_read_b128 v[214:217], v145 offset:20480
	ds_read_b128 v[218:221], v145 offset:21504
	ds_read_b128 v[222:225], v145 offset:22528
	ds_read_b128 v[226:229], v145 offset:23552
	global_load_lds_dwordx4 v[190:191], off
	v_lshl_add_u64 v[202:203], s[62:63], 0, v[130:131]
	s_mov_b32 m0, s47
	s_nop 0
	global_load_lds_dwordx4 v[202:203], off
	s_barrier
	s_waitcnt lgkmcnt(0)
	s_setprio 1
	s_waitcnt lgkmcnt(0)
	v_mfma_f32_16x16x32_bf16 v[60:63], v[146:149], v[174:177], 0
	v_mfma_f32_16x16x32_bf16 v[56:59], v[166:169], v[174:177], 0
	v_mfma_f32_16x16x32_bf16 v[44:47], v[146:149], v[182:185], 0
	v_mfma_f32_16x16x32_bf16 v[40:43], v[166:169], v[182:185], 0
	v_mfma_f32_16x16x32_bf16 v[28:31], v[146:149], v[214:217], 0
	v_mfma_f32_16x16x32_bf16 v[24:27], v[166:169], v[214:217], 0
	v_mfma_f32_16x16x32_bf16 v[12:15], v[146:149], v[222:225], 0
	v_mfma_f32_16x16x32_bf16 v[8:11], v[166:169], v[222:225], 0
	v_mfma_f32_16x16x32_bf16 v[60:63], v[150:153], v[178:181], v[60:63]
	v_mfma_f32_16x16x32_bf16 v[56:59], v[170:173], v[178:181], v[56:59]
	v_mfma_f32_16x16x32_bf16 v[44:47], v[150:153], v[186:189], v[44:47]
	v_mfma_f32_16x16x32_bf16 v[40:43], v[170:173], v[186:189], v[40:43]
	v_mfma_f32_16x16x32_bf16 v[28:31], v[150:153], v[218:221], v[28:31]
	v_mfma_f32_16x16x32_bf16 v[24:27], v[170:173], v[218:221], v[24:27]
	v_mfma_f32_16x16x32_bf16 v[12:15], v[150:153], v[226:229], v[12:15]
	v_mfma_f32_16x16x32_bf16 v[8:11], v[170:173], v[226:229], v[8:11]
	s_setprio 0
	s_barrier
	s_add_u32 s74, s58, 0x40000
	s_addc_u32 s75, s59, 0
	s_add_i32 s2, s2, s31
	v_lshl_add_u64 v[146:147], s[74:75], 0, v[158:159]
	s_mov_b32 m0, s2
	s_nop 0
	global_load_lds_dwordx4 v[146:147], off
	v_lshl_add_u64 v[146:147], s[74:75], 0, v[132:133]
	s_add_i32 m0, s2, 0x2000
	s_nop 0
	global_load_lds_dwordx4 v[146:147], off
	s_waitcnt vmcnt(6)
	s_barrier
	s_setprio 1
	v_mfma_f32_16x16x32_bf16 v[52:55], v[230:233], v[174:177], 0
	v_mfma_f32_16x16x32_bf16 v[48:51], v[238:241], v[174:177], 0
	v_mfma_f32_16x16x32_bf16 v[36:39], v[230:233], v[182:185], 0
	v_mfma_f32_16x16x32_bf16 v[32:35], v[238:241], v[182:185], 0
	v_mfma_f32_16x16x32_bf16 v[20:23], v[230:233], v[214:217], 0
	v_mfma_f32_16x16x32_bf16 v[16:19], v[238:241], v[214:217], 0
	v_mfma_f32_16x16x32_bf16 v[4:7], v[230:233], v[222:225], 0
	v_mfma_f32_16x16x32_bf16 v[0:3], v[238:241], v[222:225], 0
	v_mfma_f32_16x16x32_bf16 v[52:55], v[234:237], v[178:181], v[52:55]
	v_mfma_f32_16x16x32_bf16 v[48:51], v[242:245], v[178:181], v[48:51]
	v_mfma_f32_16x16x32_bf16 v[36:39], v[234:237], v[186:189], v[36:39]
	v_mfma_f32_16x16x32_bf16 v[32:35], v[242:245], v[186:189], v[32:35]
	v_mfma_f32_16x16x32_bf16 v[20:23], v[234:237], v[218:221], v[20:23]
	v_mfma_f32_16x16x32_bf16 v[16:19], v[242:245], v[218:221], v[16:19]
	v_mfma_f32_16x16x32_bf16 v[4:7], v[234:237], v[226:229], v[4:7]
	v_mfma_f32_16x16x32_bf16 v[0:3], v[242:245], v[226:229], v[0:3]
	s_setprio 0
	s_add_i32 s2, 0, 0x18000
	v_add_u32_e32 v140, s2, v142
	s_barrier
	ds_read_b128 v[146:149], v140
	ds_read_b128 v[150:153], v140 offset:1024
	ds_read_b128 v[166:169], v140 offset:2048
	ds_read_b128 v[170:173], v140 offset:3072
	s_add_u32 s62, s62, 0x40000
	s_addc_u32 s63, s63, 0
	s_mov_b32 m0, s48
	v_lshl_add_u64 v[204:205], s[62:63], 0, v[128:129]
	ds_read_b128 v[174:177], v145 offset:32768
	ds_read_b128 v[178:181], v145 offset:33792
	ds_read_b128 v[182:185], v145 offset:34816
	ds_read_b128 v[186:189], v145 offset:35840
	ds_read_b128 v[214:217], v145 offset:36864
	ds_read_b128 v[218:221], v145 offset:37888
	ds_read_b128 v[222:225], v145 offset:38912
	ds_read_b128 v[226:229], v145 offset:39936
	global_load_lds_dwordx4 v[204:205], off
	v_lshl_add_u64 v[204:205], s[62:63], 0, v[130:131]
	s_mov_b32 m0, s50
	s_nop 0
	global_load_lds_dwordx4 v[204:205], off
	s_waitcnt lgkmcnt(8)
	s_barrier
	s_waitcnt lgkmcnt(0)
	s_setprio 1
	s_waitcnt lgkmcnt(0)
	v_mfma_f32_16x16x32_bf16 v[124:127], v[146:149], v[174:177], v[124:127]
	v_mfma_f32_16x16x32_bf16 v[120:123], v[166:169], v[174:177], v[120:123]
	v_mfma_f32_16x16x32_bf16 v[108:111], v[146:149], v[182:185], v[108:111]
	v_mfma_f32_16x16x32_bf16 v[104:107], v[166:169], v[182:185], v[104:107]
	v_mfma_f32_16x16x32_bf16 v[92:95], v[146:149], v[214:217], v[92:95]
	v_mfma_f32_16x16x32_bf16 v[88:91], v[166:169], v[214:217], v[88:91]
	v_mfma_f32_16x16x32_bf16 v[76:79], v[146:149], v[222:225], v[76:79]
	v_mfma_f32_16x16x32_bf16 v[72:75], v[166:169], v[222:225], v[72:75]
	v_mfma_f32_16x16x32_bf16 v[124:127], v[150:153], v[178:181], v[124:127]
	v_mfma_f32_16x16x32_bf16 v[120:123], v[170:173], v[178:181], v[120:123]
	v_mfma_f32_16x16x32_bf16 v[108:111], v[150:153], v[186:189], v[108:111]
	v_mfma_f32_16x16x32_bf16 v[104:107], v[170:173], v[186:189], v[104:107]
	v_mfma_f32_16x16x32_bf16 v[92:95], v[150:153], v[218:221], v[92:95]
	v_mfma_f32_16x16x32_bf16 v[88:91], v[170:173], v[218:221], v[88:91]
	v_mfma_f32_16x16x32_bf16 v[76:79], v[150:153], v[226:229], v[76:79]
	v_mfma_f32_16x16x32_bf16 v[72:75], v[170:173], v[226:229], v[72:75]
	s_setprio 0
	s_barrier
	s_add_i32 s15, 0, 0x1c000
	s_add_i32 s2, s2, s31
	v_add_u32_e32 v140, s15, v142
	v_lshl_add_u64 v[138:139], v[138:139], 0, s[70:71]
	s_mov_b32 m0, s2
	ds_read_b128 v[230:233], v140
	ds_read_b128 v[234:237], v140 offset:1024
	ds_read_b128 v[238:241], v140 offset:2048
	ds_read_b128 v[242:245], v140 offset:3072
	global_load_lds_dwordx4 v[138:139], off
	v_lshl_add_u64 v[138:139], v[154:155], 0, s[70:71]
	s_add_i32 m0, s2, 0x2000
	s_nop 0
	global_load_lds_dwordx4 v[138:139], off
	s_barrier
	s_waitcnt lgkmcnt(0)
	s_setprio 1
	s_waitcnt lgkmcnt(0)
	v_mfma_f32_16x16x32_bf16 v[116:119], v[230:233], v[174:177], v[116:119]
	v_mfma_f32_16x16x32_bf16 v[112:115], v[238:241], v[174:177], v[112:115]
	v_mfma_f32_16x16x32_bf16 v[100:103], v[230:233], v[182:185], v[100:103]
	v_mfma_f32_16x16x32_bf16 v[96:99], v[238:241], v[182:185], v[96:99]
	v_mfma_f32_16x16x32_bf16 v[84:87], v[230:233], v[214:217], v[84:87]
	v_mfma_f32_16x16x32_bf16 v[80:83], v[238:241], v[214:217], v[80:83]
	v_mfma_f32_16x16x32_bf16 v[68:71], v[230:233], v[222:225], v[68:71]
	v_mfma_f32_16x16x32_bf16 v[64:67], v[238:241], v[222:225], v[64:67]
	v_mfma_f32_16x16x32_bf16 v[116:119], v[234:237], v[178:181], v[116:119]
	v_mfma_f32_16x16x32_bf16 v[112:115], v[242:245], v[178:181], v[112:115]
	v_mfma_f32_16x16x32_bf16 v[100:103], v[234:237], v[186:189], v[100:103]
	v_mfma_f32_16x16x32_bf16 v[96:99], v[242:245], v[186:189], v[96:99]
	v_mfma_f32_16x16x32_bf16 v[84:87], v[234:237], v[218:221], v[84:87]
	v_mfma_f32_16x16x32_bf16 v[80:83], v[242:245], v[218:221], v[80:83]
	v_mfma_f32_16x16x32_bf16 v[68:71], v[234:237], v[226:229], v[68:71]
	v_mfma_f32_16x16x32_bf16 v[64:67], v[242:245], v[226:229], v[64:67]
	s_setprio 0
	s_mov_b32 m0, s51
	v_lshl_add_u64 v[138:139], v[190:191], 0, s[70:71]
	s_barrier
	ds_read_b128 v[174:177], v145 offset:49152
	ds_read_b128 v[178:181], v145 offset:50176
	ds_read_b128 v[182:185], v145 offset:51200
	ds_read_b128 v[186:189], v145 offset:52224
	ds_read_b128 v[214:217], v145 offset:53248
	ds_read_b128 v[218:221], v145 offset:54272
	ds_read_b128 v[222:225], v145 offset:55296
	ds_read_b128 v[226:229], v145 offset:56320
	global_load_lds_dwordx4 v[138:139], off
	v_lshl_add_u64 v[138:139], v[202:203], 0, s[70:71]
	s_mov_b32 m0, s65
	s_nop 0
	global_load_lds_dwordx4 v[138:139], off
	s_barrier
	s_waitcnt lgkmcnt(0)
	s_setprio 1
	s_waitcnt lgkmcnt(0)
	v_mfma_f32_16x16x32_bf16 v[60:63], v[146:149], v[174:177], v[60:63]
	v_mfma_f32_16x16x32_bf16 v[56:59], v[166:169], v[174:177], v[56:59]
	v_mfma_f32_16x16x32_bf16 v[44:47], v[146:149], v[182:185], v[44:47]
	v_mfma_f32_16x16x32_bf16 v[40:43], v[166:169], v[182:185], v[40:43]
	v_mfma_f32_16x16x32_bf16 v[28:31], v[146:149], v[214:217], v[28:31]
	v_mfma_f32_16x16x32_bf16 v[24:27], v[166:169], v[214:217], v[24:27]
	v_mfma_f32_16x16x32_bf16 v[12:15], v[146:149], v[222:225], v[12:15]
	v_mfma_f32_16x16x32_bf16 v[8:11], v[166:169], v[222:225], v[8:11]
	v_mfma_f32_16x16x32_bf16 v[60:63], v[150:153], v[178:181], v[60:63]
	v_mfma_f32_16x16x32_bf16 v[56:59], v[170:173], v[178:181], v[56:59]
	v_mfma_f32_16x16x32_bf16 v[44:47], v[150:153], v[186:189], v[44:47]
	v_mfma_f32_16x16x32_bf16 v[40:43], v[170:173], v[186:189], v[40:43]
	v_mfma_f32_16x16x32_bf16 v[28:31], v[150:153], v[218:221], v[28:31]
	v_mfma_f32_16x16x32_bf16 v[24:27], v[170:173], v[218:221], v[24:27]
	v_mfma_f32_16x16x32_bf16 v[12:15], v[150:153], v[226:229], v[12:15]
	v_mfma_f32_16x16x32_bf16 v[8:11], v[170:173], v[226:229], v[8:11]
	s_setprio 0
	s_barrier
	s_add_u32 s58, s58, 0x40080
	s_addc_u32 s59, s59, 0
	s_add_i32 s2, s15, s31
	v_lshl_add_u64 v[138:139], s[58:59], 0, v[158:159]
	s_mov_b32 m0, s2
	s_nop 0
	global_load_lds_dwordx4 v[138:139], off
	v_lshl_add_u64 v[138:139], s[58:59], 0, v[132:133]
	s_add_i32 m0, s2, 0x2000
	s_nop 0
	global_load_lds_dwordx4 v[138:139], off
	s_waitcnt vmcnt(6)
	s_barrier
	s_setprio 1
	v_mfma_f32_16x16x32_bf16 v[52:55], v[230:233], v[174:177], v[52:55]
	v_mfma_f32_16x16x32_bf16 v[48:51], v[238:241], v[174:177], v[48:51]
	v_mfma_f32_16x16x32_bf16 v[36:39], v[230:233], v[182:185], v[36:39]
	v_mfma_f32_16x16x32_bf16 v[32:35], v[238:241], v[182:185], v[32:35]
	v_mfma_f32_16x16x32_bf16 v[20:23], v[230:233], v[214:217], v[20:23]
	v_mfma_f32_16x16x32_bf16 v[16:19], v[238:241], v[214:217], v[16:19]
	v_mfma_f32_16x16x32_bf16 v[4:7], v[230:233], v[222:225], v[4:7]
	v_mfma_f32_16x16x32_bf16 v[0:3], v[238:241], v[222:225], v[0:3]
	v_mfma_f32_16x16x32_bf16 v[52:55], v[234:237], v[178:181], v[52:55]
	v_mfma_f32_16x16x32_bf16 v[48:51], v[242:245], v[178:181], v[48:51]
	v_mfma_f32_16x16x32_bf16 v[36:39], v[234:237], v[186:189], v[36:39]
	v_mfma_f32_16x16x32_bf16 v[32:35], v[242:245], v[186:189], v[32:35]
	v_mfma_f32_16x16x32_bf16 v[20:23], v[234:237], v[218:221], v[20:23]
	v_mfma_f32_16x16x32_bf16 v[16:19], v[242:245], v[218:221], v[16:19]
	v_mfma_f32_16x16x32_bf16 v[4:7], v[234:237], v[226:229], v[4:7]
	v_mfma_f32_16x16x32_bf16 v[0:3], v[242:245], v[226:229], v[0:3]
	s_setprio 0
	s_add_i32 s72, s72, 2
	s_add_u32 s24, s24, 0x100
	s_addc_u32 s25, s25, 0
	s_add_u32 s68, s68, 0x100
	s_addc_u32 s69, s69, 0
	s_cmp_gt_u32 s72, 13
	s_barrier
	s_cbranch_scc1 .Lzp_exit2

.Lzp_exit2:
	s_lshl_b32 s11, s22, 8
	s_cmp_lg_u32 s22, s4
	s_cselect_b64 s[22:23], -1, 0
	v_add_u32_e32 v138, s11, v141
	s_mov_b64 s[24:25], -1
	s_and_b64 vcc, exec, s[22:23]
	s_cbranch_vccz .LBB0_537
	v_ashrrev_i32_e32 v139, 31, v138
	v_lshlrev_b64 v[146:147], 6, v[138:139]
	v_lshl_add_u64 v[154:155], s[94:95], 0, v[146:147]
	global_load_dwordx4 v[146:149], v[154:155], off offset:48
	global_load_dwordx4 v[150:153], v[154:155], off offset:32
	global_load_dwordx4 v[166:169], v[154:155], off offset:16
	global_load_dwordx4 v[170:173], v[154:155], off
	s_mov_b64 s[24:25], 0
	s_waitcnt vmcnt(0)
	v_add_f32_e32 v150, v150, v151
	v_add_f32_e32 v152, v152, v153
	v_mov_b32_e32 v154, v171
	v_mov_b32_e32 v155, v172
	v_mov_b32_e32 v171, v173
	v_pk_add_f32 v[154:155], v[154:155], v[170:171]
	v_mov_b32_e32 v170, v167
	v_mov_b32_e32 v171, v168
	v_mov_b32_e32 v167, v169
	v_pk_add_f32 v[166:167], v[170:171], v[166:167]
	v_pk_add_f32 v[154:155], v[154:155], v[154:155] op_sel:[0,1] op_sel_hi:[1,0]
	v_pk_add_f32 v[166:167], v[166:167], v[166:167] op_sel:[0,1] op_sel_hi:[1,0]
	v_mov_b32_e32 v155, v146
	v_mov_b32_e32 v167, v147
	v_mov_b32_e32 v151, v148
	v_mov_b32_e32 v153, v149
	v_pk_add_f32 v[146:147], v[154:155], v[166:167]
	v_pk_add_f32 v[148:149], v[150:151], v[152:153]
	s_nop 0
	v_pk_add_f32 v[146:147], v[146:147], v[148:149]
	s_nop 0
	v_add_f32_e32 v139, v146, v147
	v_fmamk_f32 v139, v139, 0x3a800000, v193
	v_cmp_gt_f32_e32 vcc, s40, v139
	v_mul_f32_e32 v140, 0x4b800000, v139
	s_nop 0
	v_cndmask_b32_e32 v139, v139, v140, vcc
	v_rsq_f32_e32 v139, v139
	s_nop 0
	v_mul_f32_e32 v140, 0x45800000, v139
	v_cndmask_b32_e32 v140, v139, v140, vcc

.LBB0_791:
	v_mov_b64_e32 v[0:1], 0x580
	s_ashr_i32 s21, s20, 31
	v_cmp_lt_i64_e32 vcc, s[22:23], v[0:1]
	s_lshl_b64 s[22:23], s[20:21], 19
	s_add_u32 s22, s96, s22
	s_addc_u32 s23, s97, s23
	s_and_b64 s[24:25], vcc, exec
	s_cselect_b32 s9, s23, s59
	s_cselect_b32 s21, s22, s58
	s_ashr_i32 s19, s18, 31
	s_lshl_b64 s[24:25], s[18:19], 19
	s_add_u32 s24, s35, s24
	s_addc_u32 s25, s47, s25
	s_and_b64 s[66:67], vcc, exec
	s_cselect_b32 s19, s25, s63
	s_cselect_b32 s29, s24, s62
	s_add_u32 s58, s58, 0x40080
	s_addc_u32 s59, s59, 0
	s_add_u32 s43, s62, 0x100
	s_addc_u32 s51, s63, 0
	s_mov_b32 s75, -2
	s_add_u32 s62, s58, 0xfffc0080
	s_addc_u32 s63, s59, -1
	s_add_i32 s76, 0, 0x10000
	v_add_u32_e32 v138, s76, v142
	ds_read_b128 v[146:149], v138
	ds_read_b128 v[150:153], v138 offset:1024
	ds_read_b128 v[166:169], v138 offset:2048
	ds_read_b128 v[170:173], v138 offset:3072
	s_cmp_eq_u32 s75, 12
	s_cselect_b32 s67, s9, s63
	s_cselect_b32 s66, s21, s62
	s_cselect_b32 s63, s19, s51
	s_cselect_b32 s62, s29, s43
	v_lshl_add_u64 v[138:139], s[58:59], 0, v[134:135]
	s_add_i32 m0, s48, 0xc000
	ds_read_b128 v[174:177], v145
	ds_read_b128 v[178:181], v145 offset:1024
	ds_read_b128 v[182:185], v145 offset:2048
	ds_read_b128 v[186:189], v145 offset:3072
	ds_read_b128 v[214:217], v145 offset:4096
	ds_read_b128 v[218:221], v145 offset:5120
	ds_read_b128 v[222:225], v145 offset:6144
	ds_read_b128 v[226:229], v145 offset:7168
	global_load_lds_dwordx4 v[138:139], off
	v_lshl_add_u64 v[138:139], s[58:59], 0, v[136:137]
	s_add_i32 m0, s48, 0xe000
	s_nop 0
	global_load_lds_dwordx4 v[138:139], off
	s_waitcnt lgkmcnt(8)
	s_barrier
	s_waitcnt lgkmcnt(0)
	s_setprio 1
	s_waitcnt lgkmcnt(0)
	v_mfma_f32_16x16x32_bf16 v[124:127], v[146:149], v[174:177], 0
	v_mfma_f32_16x16x32_bf16 v[116:119], v[166:169], v[174:177], 0
	v_mfma_f32_16x16x32_bf16 v[108:111], v[146:149], v[182:185], 0
	v_mfma_f32_16x16x32_bf16 v[100:103], v[166:169], v[182:185], 0
	v_mfma_f32_16x16x32_bf16 v[92:95], v[146:149], v[214:217], 0
	v_mfma_f32_16x16x32_bf16 v[84:87], v[166:169], v[214:217], 0
	v_mfma_f32_16x16x32_bf16 v[76:79], v[146:149], v[222:225], 0
	v_mfma_f32_16x16x32_bf16 v[68:71], v[166:169], v[222:225], 0
	v_mfma_f32_16x16x32_bf16 v[124:127], v[150:153], v[178:181], v[124:127]
	v_mfma_f32_16x16x32_bf16 v[116:119], v[170:173], v[178:181], v[116:119]
	v_mfma_f32_16x16x32_bf16 v[108:111], v[150:153], v[186:189], v[108:111]
	v_mfma_f32_16x16x32_bf16 v[100:103], v[170:173], v[186:189], v[100:103]
	v_mfma_f32_16x16x32_bf16 v[92:95], v[150:153], v[218:221], v[92:95]
	v_mfma_f32_16x16x32_bf16 v[84:87], v[170:173], v[218:221], v[84:87]
	v_mfma_f32_16x16x32_bf16 v[76:79], v[150:153], v[226:229], v[76:79]
	v_mfma_f32_16x16x32_bf16 v[68:71], v[170:173], v[226:229], v[68:71]
	s_setprio 0
	s_barrier
	s_add_i32 s78, 0, 0x14000
	v_add_u32_e32 v138, s78, v142
	s_add_i32 s76, s76, s31
	ds_read_b128 v[230:233], v138
	ds_read_b128 v[234:237], v138 offset:1024
	ds_read_b128 v[238:241], v138 offset:2048
	ds_read_b128 v[242:245], v138 offset:3072
	v_lshl_add_u64 v[138:139], s[62:63], 0, v[158:159]
	s_mov_b32 m0, s76
	v_lshl_add_u64 v[154:155], s[62:63], 0, v[132:133]
	global_load_lds_dwordx4 v[138:139], off
	s_add_i32 m0, s76, 0x2000
	s_nop 0
	global_load_lds_dwordx4 v[154:155], off
	s_barrier
	s_waitcnt lgkmcnt(0)
	s_setprio 1
	s_waitcnt lgkmcnt(0)
	v_mfma_f32_16x16x32_bf16 v[120:123], v[230:233], v[174:177], 0
	v_mfma_f32_16x16x32_bf16 v[112:115], v[238:241], v[174:177], 0
	v_mfma_f32_16x16x32_bf16 v[104:107], v[230:233], v[182:185], 0
	v_mfma_f32_16x16x32_bf16 v[96:99], v[238:241], v[182:185], 0
	v_mfma_f32_16x16x32_bf16 v[88:91], v[230:233], v[214:217], 0
	v_mfma_f32_16x16x32_bf16 v[80:83], v[238:241], v[214:217], 0
	v_mfma_f32_16x16x32_bf16 v[72:75], v[230:233], v[222:225], 0
	v_mfma_f32_16x16x32_bf16 v[64:67], v[238:241], v[222:225], 0
	v_mfma_f32_16x16x32_bf16 v[120:123], v[234:237], v[178:181], v[120:123]
	v_mfma_f32_16x16x32_bf16 v[112:115], v[242:245], v[178:181], v[112:115]
	v_mfma_f32_16x16x32_bf16 v[104:107], v[234:237], v[186:189], v[104:107]
	v_mfma_f32_16x16x32_bf16 v[96:99], v[242:245], v[186:189], v[96:99]
	v_mfma_f32_16x16x32_bf16 v[88:91], v[234:237], v[218:221], v[88:91]
	v_mfma_f32_16x16x32_bf16 v[80:83], v[242:245], v[218:221], v[80:83]
	v_mfma_f32_16x16x32_bf16 v[72:75], v[234:237], v[226:229], v[72:75]
	v_mfma_f32_16x16x32_bf16 v[64:67], v[242:245], v[226:229], v[64:67]
	s_setprio 0
	s_mov_b32 m0, s48
	v_lshl_add_u64 v[190:191], s[66:67], 0, v[128:129]
	s_barrier
	ds_read_b128 v[174:177], v145 offset:16384
	ds_read_b128 v[178:181], v145 offset:17408
	ds_read_b128 v[182:185], v145 offset:18432
	ds_read_b128 v[186:189], v145 offset:19456
	ds_read_b128 v[214:217], v145 offset:20480
	ds_read_b128 v[218:221], v145 offset:21504
	ds_read_b128 v[222:225], v145 offset:22528
	ds_read_b128 v[226:229], v145 offset:23552
	global_load_lds_dwordx4 v[190:191], off
	v_lshl_add_u64 v[202:203], s[66:67], 0, v[130:131]
	s_mov_b32 m0, s50
	s_nop 0
	global_load_lds_dwordx4 v[202:203], off
	s_barrier
	s_waitcnt lgkmcnt(0)
	s_setprio 1
	s_waitcnt lgkmcnt(0)
	v_mfma_f32_16x16x32_bf16 v[60:63], v[146:149], v[174:177], 0
	v_mfma_f32_16x16x32_bf16 v[52:55], v[166:169], v[174:177], 0
	v_mfma_f32_16x16x32_bf16 v[44:47], v[146:149], v[182:185], 0
	v_mfma_f32_16x16x32_bf16 v[36:39], v[166:169], v[182:185], 0
	v_mfma_f32_16x16x32_bf16 v[28:31], v[146:149], v[214:217], 0
	v_mfma_f32_16x16x32_bf16 v[20:23], v[166:169], v[214:217], 0
	v_mfma_f32_16x16x32_bf16 v[12:15], v[146:149], v[222:225], 0
	v_mfma_f32_16x16x32_bf16 v[4:7], v[166:169], v[222:225], 0
	v_mfma_f32_16x16x32_bf16 v[60:63], v[150:153], v[178:181], v[60:63]
	v_mfma_f32_16x16x32_bf16 v[52:55], v[170:173], v[178:181], v[52:55]
	v_mfma_f32_16x16x32_bf16 v[44:47], v[150:153], v[186:189], v[44:47]
	v_mfma_f32_16x16x32_bf16 v[36:39], v[170:173], v[186:189], v[36:39]
	v_mfma_f32_16x16x32_bf16 v[28:31], v[150:153], v[218:221], v[28:31]
	v_mfma_f32_16x16x32_bf16 v[20:23], v[170:173], v[218:221], v[20:23]
	v_mfma_f32_16x16x32_bf16 v[12:15], v[150:153], v[226:229], v[12:15]
	v_mfma_f32_16x16x32_bf16 v[4:7], v[170:173], v[226:229], v[4:7]
	s_setprio 0
	s_barrier
	s_add_u32 s76, s62, 0x40000
	s_addc_u32 s77, s63, 0
	s_add_i32 s78, s78, s31
	v_lshl_add_u64 v[146:147], s[76:77], 0, v[158:159]
	s_mov_b32 m0, s78
	s_nop 0
	global_load_lds_dwordx4 v[146:147], off
	v_lshl_add_u64 v[146:147], s[76:77], 0, v[132:133]
	s_add_i32 m0, s78, 0x2000
	s_nop 0
	global_load_lds_dwordx4 v[146:147], off
	s_waitcnt vmcnt(6)
	s_barrier
	s_setprio 1
	v_mfma_f32_16x16x32_bf16 v[56:59], v[230:233], v[174:177], 0
	v_mfma_f32_16x16x32_bf16 v[48:51], v[238:241], v[174:177], 0
	v_mfma_f32_16x16x32_bf16 v[40:43], v[230:233], v[182:185], 0
	v_mfma_f32_16x16x32_bf16 v[32:35], v[238:241], v[182:185], 0
	v_mfma_f32_16x16x32_bf16 v[24:27], v[230:233], v[214:217], 0
	v_mfma_f32_16x16x32_bf16 v[16:19], v[238:241], v[214:217], 0
	v_mfma_f32_16x16x32_bf16 v[8:11], v[230:233], v[222:225], 0
	v_mfma_f32_16x16x32_bf16 v[0:3], v[238:241], v[222:225], 0
	v_mfma_f32_16x16x32_bf16 v[56:59], v[234:237], v[178:181], v[56:59]
	v_mfma_f32_16x16x32_bf16 v[48:51], v[242:245], v[178:181], v[48:51]
	v_mfma_f32_16x16x32_bf16 v[40:43], v[234:237], v[186:189], v[40:43]
	v_mfma_f32_16x16x32_bf16 v[32:35], v[242:245], v[186:189], v[32:35]
	v_mfma_f32_16x16x32_bf16 v[24:27], v[234:237], v[218:221], v[24:27]
	v_mfma_f32_16x16x32_bf16 v[16:19], v[242:245], v[218:221], v[16:19]
	v_mfma_f32_16x16x32_bf16 v[8:11], v[234:237], v[226:229], v[8:11]
	v_mfma_f32_16x16x32_bf16 v[0:3], v[242:245], v[226:229], v[0:3]
	s_setprio 0
	s_add_i32 s76, 0, 0x18000
	v_add_u32_e32 v140, s76, v142
	s_barrier
	ds_read_b128 v[146:149], v140
	ds_read_b128 v[150:153], v140 offset:1024
	ds_read_b128 v[166:169], v140 offset:2048
	ds_read_b128 v[170:173], v140 offset:3072
	s_add_u32 s66, s66, 0x40000
	s_addc_u32 s67, s67, 0
	s_mov_b32 m0, s65
	v_lshl_add_u64 v[204:205], s[66:67], 0, v[128:129]
	ds_read_b128 v[174:177], v145 offset:32768
	ds_read_b128 v[178:181], v145 offset:33792
	ds_read_b128 v[182:185], v145 offset:34816
	ds_read_b128 v[186:189], v145 offset:35840
	ds_read_b128 v[214:217], v145 offset:36864
	ds_read_b128 v[218:221], v145 offset:37888
	ds_read_b128 v[222:225], v145 offset:38912
	ds_read_b128 v[226:229], v145 offset:39936
	global_load_lds_dwordx4 v[204:205], off
	v_lshl_add_u64 v[204:205], s[66:67], 0, v[130:131]
	s_mov_b32 m0, s68
	s_nop 0
	global_load_lds_dwordx4 v[204:205], off
	s_waitcnt lgkmcnt(8)
	s_barrier
	s_waitcnt lgkmcnt(0)
	s_setprio 1
	s_waitcnt lgkmcnt(0)
	v_mfma_f32_16x16x32_bf16 v[124:127], v[146:149], v[174:177], v[124:127]
	v_mfma_f32_16x16x32_bf16 v[116:119], v[166:169], v[174:177], v[116:119]
	v_mfma_f32_16x16x32_bf16 v[108:111], v[146:149], v[182:185], v[108:111]
	v_mfma_f32_16x16x32_bf16 v[100:103], v[166:169], v[182:185], v[100:103]
	v_mfma_f32_16x16x32_bf16 v[92:95], v[146:149], v[214:217], v[92:95]
	v_mfma_f32_16x16x32_bf16 v[84:87], v[166:169], v[214:217], v[84:87]
	v_mfma_f32_16x16x32_bf16 v[76:79], v[146:149], v[222:225], v[76:79]
	v_mfma_f32_16x16x32_bf16 v[68:71], v[166:169], v[222:225], v[68:71]
	v_mfma_f32_16x16x32_bf16 v[124:127], v[150:153], v[178:181], v[124:127]
	v_mfma_f32_16x16x32_bf16 v[116:119], v[170:173], v[178:181], v[116:119]
	v_mfma_f32_16x16x32_bf16 v[108:111], v[150:153], v[186:189], v[108:111]
	v_mfma_f32_16x16x32_bf16 v[100:103], v[170:173], v[186:189], v[100:103]
	v_mfma_f32_16x16x32_bf16 v[92:95], v[150:153], v[218:221], v[92:95]
	v_mfma_f32_16x16x32_bf16 v[84:87], v[170:173], v[218:221], v[84:87]
	v_mfma_f32_16x16x32_bf16 v[76:79], v[150:153], v[226:229], v[76:79]
	v_mfma_f32_16x16x32_bf16 v[68:71], v[170:173], v[226:229], v[68:71]
	s_setprio 0
	s_barrier
	s_add_i32 s66, 0, 0x1c000
	s_add_i32 s67, s76, s31
	v_add_u32_e32 v140, s66, v142
	v_lshl_add_u64 v[138:139], v[138:139], 0, s[70:71]
	s_mov_b32 m0, s67
	ds_read_b128 v[230:233], v140
	ds_read_b128 v[234:237], v140 offset:1024
	ds_read_b128 v[238:241], v140 offset:2048
	ds_read_b128 v[242:245], v140 offset:3072
	global_load_lds_dwordx4 v[138:139], off
	v_lshl_add_u64 v[138:139], v[154:155], 0, s[70:71]
	s_add_i32 m0, s67, 0x2000
	s_nop 0
	global_load_lds_dwordx4 v[138:139], off
	s_barrier
	s_waitcnt lgkmcnt(0)
	s_setprio 1
	s_waitcnt lgkmcnt(0)
	v_mfma_f32_16x16x32_bf16 v[120:123], v[230:233], v[174:177], v[120:123]
	v_mfma_f32_16x16x32_bf16 v[112:115], v[238:241], v[174:177], v[112:115]
	v_mfma_f32_16x16x32_bf16 v[104:107], v[230:233], v[182:185], v[104:107]
	v_mfma_f32_16x16x32_bf16 v[96:99], v[238:241], v[182:185], v[96:99]
	v_mfma_f32_16x16x32_bf16 v[88:91], v[230:233], v[214:217], v[88:91]
	v_mfma_f32_16x16x32_bf16 v[80:83], v[238:241], v[214:217], v[80:83]
	v_mfma_f32_16x16x32_bf16 v[72:75], v[230:233], v[222:225], v[72:75]
	v_mfma_f32_16x16x32_bf16 v[64:67], v[238:241], v[222:225], v[64:67]
	v_mfma_f32_16x16x32_bf16 v[120:123], v[234:237], v[178:181], v[120:123]
	v_mfma_f32_16x16x32_bf16 v[112:115], v[242:245], v[178:181], v[112:115]
	v_mfma_f32_16x16x32_bf16 v[104:107], v[234:237], v[186:189], v[104:107]
	v_mfma_f32_16x16x32_bf16 v[96:99], v[242:245], v[186:189], v[96:99]
	v_mfma_f32_16x16x32_bf16 v[88:91], v[234:237], v[218:221], v[88:91]
	v_mfma_f32_16x16x32_bf16 v[80:83], v[242:245], v[218:221], v[80:83]
	v_mfma_f32_16x16x32_bf16 v[72:75], v[234:237], v[226:229], v[72:75]
	v_mfma_f32_16x16x32_bf16 v[64:67], v[242:245], v[226:229], v[64:67]
	s_setprio 0
	s_mov_b32 m0, s69
	v_lshl_add_u64 v[138:139], v[190:191], 0, s[70:71]
	s_barrier
	ds_read_b128 v[174:177], v145 offset:49152
	ds_read_b128 v[178:181], v145 offset:50176
	ds_read_b128 v[182:185], v145 offset:51200
	ds_read_b128 v[186:189], v145 offset:52224
	ds_read_b128 v[214:217], v145 offset:53248
	ds_read_b128 v[218:221], v145 offset:54272
	ds_read_b128 v[222:225], v145 offset:55296
	ds_read_b128 v[226:229], v145 offset:56320
	global_load_lds_dwordx4 v[138:139], off
	v_lshl_add_u64 v[138:139], v[202:203], 0, s[70:71]
	s_mov_b32 m0, s72
	s_nop 0
	global_load_lds_dwordx4 v[138:139], off
	s_barrier
	s_waitcnt lgkmcnt(0)
	s_setprio 1
	s_waitcnt lgkmcnt(0)
	v_mfma_f32_16x16x32_bf16 v[60:63], v[146:149], v[174:177], v[60:63]
	v_mfma_f32_16x16x32_bf16 v[52:55], v[166:169], v[174:177], v[52:55]
	v_mfma_f32_16x16x32_bf16 v[44:47], v[146:149], v[182:185], v[44:47]
	v_mfma_f32_16x16x32_bf16 v[36:39], v[166:169], v[182:185], v[36:39]
	v_mfma_f32_16x16x32_bf16 v[28:31], v[146:149], v[214:217], v[28:31]
	v_mfma_f32_16x16x32_bf16 v[20:23], v[166:169], v[214:217], v[20:23]
	v_mfma_f32_16x16x32_bf16 v[12:15], v[146:149], v[222:225], v[12:15]
	v_mfma_f32_16x16x32_bf16 v[4:7], v[166:169], v[222:225], v[4:7]
	v_mfma_f32_16x16x32_bf16 v[60:63], v[150:153], v[178:181], v[60:63]
	v_mfma_f32_16x16x32_bf16 v[52:55], v[170:173], v[178:181], v[52:55]
	v_mfma_f32_16x16x32_bf16 v[44:47], v[150:153], v[186:189], v[44:47]
	v_mfma_f32_16x16x32_bf16 v[36:39], v[170:173], v[186:189], v[36:39]
	v_mfma_f32_16x16x32_bf16 v[28:31], v[150:153], v[218:221], v[28:31]
	v_mfma_f32_16x16x32_bf16 v[20:23], v[170:173], v[218:221], v[20:23]
	v_mfma_f32_16x16x32_bf16 v[12:15], v[150:153], v[226:229], v[12:15]
	v_mfma_f32_16x16x32_bf16 v[4:7], v[170:173], v[226:229], v[4:7]
	s_setprio 0
	s_barrier
	s_add_u32 s62, s62, 0x40080
	s_addc_u32 s63, s63, 0
	s_add_i32 s66, s66, s31
	v_lshl_add_u64 v[138:139], s[62:63], 0, v[158:159]
	s_mov_b32 m0, s66
	s_nop 0
	global_load_lds_dwordx4 v[138:139], off
	v_lshl_add_u64 v[138:139], s[62:63], 0, v[132:133]
	s_add_i32 m0, s66, 0x2000
	s_nop 0
	global_load_lds_dwordx4 v[138:139], off
	s_waitcnt vmcnt(6)
	s_barrier
	s_setprio 1
	v_mfma_f32_16x16x32_bf16 v[56:59], v[230:233], v[174:177], v[56:59]
	v_mfma_f32_16x16x32_bf16 v[48:51], v[238:241], v[174:177], v[48:51]
	v_mfma_f32_16x16x32_bf16 v[40:43], v[230:233], v[182:185], v[40:43]
	v_mfma_f32_16x16x32_bf16 v[32:35], v[238:241], v[182:185], v[32:35]
	v_mfma_f32_16x16x32_bf16 v[24:27], v[230:233], v[214:217], v[24:27]
	v_mfma_f32_16x16x32_bf16 v[16:19], v[238:241], v[214:217], v[16:19]
	v_mfma_f32_16x16x32_bf16 v[8:11], v[230:233], v[222:225], v[8:11]
	v_mfma_f32_16x16x32_bf16 v[0:3], v[238:241], v[222:225], v[0:3]
	v_mfma_f32_16x16x32_bf16 v[56:59], v[234:237], v[178:181], v[56:59]
	v_mfma_f32_16x16x32_bf16 v[48:51], v[242:245], v[178:181], v[48:51]
	v_mfma_f32_16x16x32_bf16 v[40:43], v[234:237], v[186:189], v[40:43]
	v_mfma_f32_16x16x32_bf16 v[32:35], v[242:245], v[186:189], v[32:35]
	v_mfma_f32_16x16x32_bf16 v[24:27], v[234:237], v[218:221], v[24:27]
	v_mfma_f32_16x16x32_bf16 v[16:19], v[242:245], v[218:221], v[16:19]
	v_mfma_f32_16x16x32_bf16 v[8:11], v[234:237], v[226:229], v[8:11]
	v_mfma_f32_16x16x32_bf16 v[0:3], v[242:245], v[226:229], v[0:3]
	s_setprio 0
	s_add_i32 s75, s75, 2
	s_add_u32 s58, s58, 0x100
	s_addc_u32 s59, s59, 0
	s_add_u32 s43, s43, 0x100
	s_addc_u32 s51, s51, 0
	s_cmp_gt_u32 s75, 13
	s_barrier
	s_cbranch_scc1 .Lzp_exit3

.Lzp_exit3:
	s_lshl_b32 s19, s28, 8
	s_cmp_lg_u32 s28, s4
	s_cselect_b64 s[28:29], -1, 0
	v_add_u32_e32 v138, s19, v141
	s_mov_b64 s[58:59], -1
	s_and_b64 vcc, exec, s[28:29]
	s_cbranch_vccz .LBB0_795
	v_ashrrev_i32_e32 v139, 31, v138
	v_lshlrev_b64 v[146:147], 6, v[138:139]
	v_lshl_add_u64 v[154:155], s[94:95], 0, v[146:147]
	global_load_dwordx4 v[146:149], v[154:155], off offset:48
	global_load_dwordx4 v[150:153], v[154:155], off offset:32
	global_load_dwordx4 v[166:169], v[154:155], off offset:16
	global_load_dwordx4 v[170:173], v[154:155], off
	s_mov_b64 s[58:59], 0
	s_waitcnt vmcnt(0)
	v_add_f32_e32 v150, v150, v151
	v_add_f32_e32 v152, v152, v153
	v_mov_b32_e32 v154, v171
	v_mov_b32_e32 v155, v172
	v_mov_b32_e32 v171, v173
	v_pk_add_f32 v[154:155], v[154:155], v[170:171]
	v_mov_b32_e32 v170, v167
	v_mov_b32_e32 v171, v168
	v_mov_b32_e32 v167, v169
	v_pk_add_f32 v[166:167], v[170:171], v[166:167]
	v_pk_add_f32 v[154:155], v[154:155], v[154:155] op_sel:[0,1] op_sel_hi:[1,0]
	v_pk_add_f32 v[166:167], v[166:167], v[166:167] op_sel:[0,1] op_sel_hi:[1,0]
	v_mov_b32_e32 v155, v146
	v_mov_b32_e32 v167, v147
	v_mov_b32_e32 v151, v148
	v_mov_b32_e32 v153, v149
	v_pk_add_f32 v[146:147], v[154:155], v[166:167]
	v_pk_add_f32 v[148:149], v[150:151], v[152:153]
	s_nop 0
	v_pk_add_f32 v[146:147], v[146:147], v[148:149]
	s_nop 0
	v_add_f32_e32 v139, v146, v147
	v_fmamk_f32 v139, v139, 0x3a800000, v193
	v_cmp_gt_f32_e32 vcc, s40, v139
	v_mul_f32_e32 v140, 0x4b800000, v139
	s_nop 0
	v_cndmask_b32_e32 v139, v139, v140, vcc
	v_rsq_f32_e32 v139, v139
	s_nop 0
	v_mul_f32_e32 v140, 0x45800000, v139
	v_cndmask_b32_e32 v140, v139, v140, vcc
